# decode attention rewritten by hand: 6 register sets (5 groups in flight), saddr addressing, V rows loaded once per lane-row pair and shared via v_permlane16_swap (4 loads per group instead of 6); same
# speedup vs baseline: 1.0325x; 1.0205x over previous
.LBB0_756:
	v_and_b32_e32 v3, 15, v228
	v_lshrrev_b32_e32 v5, 5, v228
	v_bfe_u32 v240, v228, 4, 1
	s_and_b32 s33, s22, -8
	s_lshl_b32 s33, s33, 2
	s_load_dwordx8 s[24:31], s[52:53], s33
	s_lshr_b32 s2, s22, 4
	s_lshl_b32 s2, s2, 13
	v_lshlrev_b32_e32 v241, 8, v240
	v_lshl_add_u32 v241, v3, 4, v241
	v_add_u32_e32 v242, s2, v241
	v_add_u32_e32 v243, 0x1000, v242
	global_load_dwordx4 v[40:43], v242, s[14:15]
	global_load_dwordx4 v[44:47], v242, s[14:15] offset:2048
	global_load_dwordx4 v[48:51], v243, s[14:15]
	global_load_dwordx4 v[52:55], v243, s[14:15] offset:2048
	s_bfe_u32 s33, s22, 0x10002
	s_lshl_b32 s60, s33, 6
	s_lshl_b32 s33, s33, 17
	s_lshl_b32 s57, s89, 2
	s_add_i32 s33, s33, s57
	v_lshlrev_b32_e32 v60, 4, v3
	v_lshl_add_u32 v60, v5, 11, v60
	v_add_u32_e32 v60, s33, v60
	v_lshl_add_u32 v59, v240, 8, v60
	v_and_b32_e32 v241, 1, v228
	v_and_b32_e32 v244, 2, v228
	v_cmp_eq_u32_e64 s[8:9], 0, v241
	v_cmp_eq_u32_e64 s[34:35], 0, v244
	v_and_b32_e32 v62, 3, v228
	v_sub_u32_e32 v62, v62, v5
	s_bfe_u32 s37, s22, 0x10003
	v_mov_b32_e32 v8, 0
	v_mov_b32_e32 v9, 0
	v_mov_b32_e32 v10, 0
	v_mov_b32_e32 v11, 0
	v_mov_b32_e32 v12, 0
	v_mov_b32_e32 v13, 0
	v_mov_b32_e32 v14, 0
	v_mov_b32_e32 v15, 0
	v_mov_b32_e32 v16, 0
	v_mov_b32_e32 v17, 0
	v_mov_b32_e32 v18, 0
	v_mov_b32_e32 v19, 0
	v_mov_b32_e32 v20, 0
	v_mov_b32_e32 v21, 0
	v_mov_b32_e32 v22, 0
	v_mov_b32_e32 v23, 0
	v_mov_b32_e32 v24, 0
	v_mov_b32_e32 v25, 0
	v_mov_b32_e32 v26, 0
	v_mov_b32_e32 v27, 0
	v_mov_b32_e32 v28, 0
	v_mov_b32_e32 v29, 0
	v_mov_b32_e32 v30, 0
	v_mov_b32_e32 v31, 0
	v_mov_b32_e32 v32, 0
	v_mov_b32_e32 v33, 0
	v_mov_b32_e32 v34, 0
	v_mov_b32_e32 v35, 0
	v_mov_b32_e32 v36, 0
	v_mov_b32_e32 v37, 0
	v_mov_b32_e32 v38, 0
	v_mov_b32_e32 v39, 0
	v_mov_b32_e32 v56, 0xf149f2ca
	v_mov_b32_e32 v57, 0
	s_mov_b32 s23, -1
	s_mov_b32 s39, -1
	s_waitcnt lgkmcnt(0)
	s_add_i32 s23, s23, 1
	s_and_b32 s33, s23, 15
	s_cmp_eq_u32 s33, 0
	s_cbranch_scc1 .Ldq_np_1
	s_add_u32 s4, s4, 0x2000
	s_addc_u32 s5, s5, 0
	s_add_u32 s6, s6, 0x2000
	s_addc_u32 s7, s7, 0
.Ldq_npret_2:
	global_load_dwordx4 v[64:67], v59, s[4:5] offset:-4096 nt
	global_load_dwordx4 v[68:71], v59, s[6:7] offset:-4096 nt
	global_load_dwordx4 v[72:75], v59, s[4:5] nt
	global_load_dwordx4 v[76:79], v59, s[6:7] nt
	s_add_i32 s23, s23, 1
	s_and_b32 s33, s23, 15
	s_cmp_eq_u32 s33, 0
	s_cbranch_scc1 .Ldq_np_3
	s_add_u32 s4, s4, 0x2000
	s_addc_u32 s5, s5, 0
	s_add_u32 s6, s6, 0x2000
	s_addc_u32 s7, s7, 0
.Ldq_npret_4:
	global_load_dwordx4 v[80:83], v59, s[4:5] offset:-4096 nt
	global_load_dwordx4 v[84:87], v59, s[6:7] offset:-4096 nt
	global_load_dwordx4 v[88:91], v59, s[4:5] nt
	global_load_dwordx4 v[92:95], v59, s[6:7] nt
	s_add_i32 s23, s23, 1
	s_and_b32 s33, s23, 15
	s_cmp_eq_u32 s33, 0
	s_cbranch_scc1 .Ldq_np_5
	s_add_u32 s4, s4, 0x2000
	s_addc_u32 s5, s5, 0
	s_add_u32 s6, s6, 0x2000
	s_addc_u32 s7, s7, 0
.Ldq_npret_6:
	global_load_dwordx4 v[96:99], v59, s[4:5] offset:-4096 nt
	global_load_dwordx4 v[100:103], v59, s[6:7] offset:-4096 nt
	global_load_dwordx4 v[104:107], v59, s[4:5] nt
	global_load_dwordx4 v[108:111], v59, s[6:7] nt
	s_add_i32 s23, s23, 1
	s_and_b32 s33, s23, 15
	s_cmp_eq_u32 s33, 0
	s_cbranch_scc1 .Ldq_np_7
	s_add_u32 s4, s4, 0x2000
	s_addc_u32 s5, s5, 0
	s_add_u32 s6, s6, 0x2000
	s_addc_u32 s7, s7, 0
.Ldq_npret_8:
	global_load_dwordx4 v[112:115], v59, s[4:5] offset:-4096 nt
	global_load_dwordx4 v[116:119], v59, s[6:7] offset:-4096 nt
	global_load_dwordx4 v[120:123], v59, s[4:5] nt
	global_load_dwordx4 v[124:127], v59, s[6:7] nt
	s_add_i32 s23, s23, 1
	s_and_b32 s33, s23, 15
	s_cmp_eq_u32 s33, 0
	s_cbranch_scc1 .Ldq_np_9
	s_add_u32 s4, s4, 0x2000
	s_addc_u32 s5, s5, 0
	s_add_u32 s6, s6, 0x2000
	s_addc_u32 s7, s7, 0
.Ldq_npret_10:
	global_load_dwordx4 v[128:131], v59, s[4:5] offset:-4096 nt
	global_load_dwordx4 v[132:135], v59, s[6:7] offset:-4096 nt
	global_load_dwordx4 v[136:139], v59, s[4:5] nt
	global_load_dwordx4 v[140:143], v59, s[6:7] nt
	s_movk_i32 s56, 20
.Ldq_loop_11:
	s_add_i32 s23, s23, 1
	s_and_b32 s33, s23, 15
	s_cmp_eq_u32 s33, 0
	s_cbranch_scc1 .Ldq_np_12
	s_add_u32 s4, s4, 0x2000
	s_addc_u32 s5, s5, 0
	s_add_u32 s6, s6, 0x2000
	s_addc_u32 s7, s7, 0
.Ldq_npret_13:
	global_load_dwordx4 v[144:147], v59, s[4:5] offset:-4096 nt
	global_load_dwordx4 v[148:151], v59, s[6:7] offset:-4096 nt
	global_load_dwordx4 v[152:155], v59, s[4:5] nt
	global_load_dwordx4 v[156:159], v59, s[6:7] nt
	s_add_i32 s39, s39, 1
	s_lshr_b32 s33, s39, 4
	s_cmp_eq_u32 s33, 7
	s_cselect_b32 s36, s37, 0
	s_waitcnt vmcnt(21)
	v_mul_f32_e32 v212, v40, v64
	v_mul_f32_e32 v213, v44, v64
	v_mul_f32_e32 v214, v48, v64
	v_mul_f32_e32 v215, v52, v64
	v_mul_f32_e32 v216, v40, v72
	v_mul_f32_e32 v217, v44, v72
	v_mul_f32_e32 v218, v48, v72
	v_mul_f32_e32 v219, v52, v72
	v_fmac_f32_e32 v212, v65, v41
	v_fmac_f32_e32 v213, v65, v45
	v_fmac_f32_e32 v214, v65, v49
	v_fmac_f32_e32 v215, v65, v53
	v_fmac_f32_e32 v216, v73, v41
	v_fmac_f32_e32 v217, v73, v45
	v_fmac_f32_e32 v218, v73, v49
	v_fmac_f32_e32 v219, v73, v53
	v_fmac_f32_e32 v212, v66, v42
	v_fmac_f32_e32 v213, v66, v46
	v_fmac_f32_e32 v214, v66, v50
	v_fmac_f32_e32 v215, v66, v54
	v_fmac_f32_e32 v216, v74, v42
	v_fmac_f32_e32 v217, v74, v46
	v_fmac_f32_e32 v218, v74, v50
	v_fmac_f32_e32 v219, v74, v54
	v_fmac_f32_e32 v212, v67, v43
	v_fmac_f32_e32 v213, v67, v47
	v_fmac_f32_e32 v214, v67, v51
	v_fmac_f32_e32 v215, v67, v55
	v_fmac_f32_e32 v216, v75, v43
	v_fmac_f32_e32 v217, v75, v47
	v_fmac_f32_e32 v218, v75, v51
	v_fmac_f32_e32 v219, v75, v55
	v_cndmask_b32_e64 v241, v212, v213, s[8:9]
	v_cndmask_b32_e64 v245, v216, v217, s[8:9]
	v_cndmask_b32_e64 v243, v214, v215, s[8:9]
	v_cndmask_b32_e64 v247, v218, v219, s[8:9]
	v_cndmask_b32_e64 v240, v213, v212, s[8:9]
	v_cndmask_b32_e64 v244, v217, v216, s[8:9]
	v_cndmask_b32_e64 v242, v215, v214, s[8:9]
	v_cndmask_b32_e64 v246, v219, v218, s[8:9]
	v_add_f32_dpp v240, v241, v240 quad_perm:[1,0,3,2] row_mask:0xf bank_mask:0xf bound_ctrl:1
	v_add_f32_dpp v244, v245, v244 quad_perm:[1,0,3,2] row_mask:0xf bank_mask:0xf bound_ctrl:1
	v_add_f32_dpp v242, v243, v242 quad_perm:[1,0,3,2] row_mask:0xf bank_mask:0xf bound_ctrl:1
	v_add_f32_dpp v246, v247, v246 quad_perm:[1,0,3,2] row_mask:0xf bank_mask:0xf bound_ctrl:1
	v_cndmask_b32_e64 v213, v240, v242, s[34:35]
	v_cndmask_b32_e64 v217, v244, v246, s[34:35]
	v_cndmask_b32_e64 v212, v242, v240, s[34:35]
	v_cndmask_b32_e64 v216, v246, v244, s[34:35]
	s_nop 0
	v_add_f32_dpp v212, v213, v212 quad_perm:[2,3,0,1] row_mask:0xf bank_mask:0xf bound_ctrl:1
	v_add_f32_dpp v216, v217, v216 quad_perm:[2,3,0,1] row_mask:0xf bank_mask:0xf bound_ctrl:1
	s_nop 0
	v_add_f32_dpp v212, v212, v212 row_ror:4 row_mask:0xf bank_mask:0xf bound_ctrl:1
	v_add_f32_dpp v216, v216, v216 row_ror:4 row_mask:0xf bank_mask:0xf bound_ctrl:1
	s_nop 0
	v_add_f32_dpp v212, v212, v212 row_ror:8 row_mask:0xf bank_mask:0xf bound_ctrl:1
	v_add_f32_dpp v216, v216, v216 row_ror:8 row_mask:0xf bank_mask:0xf bound_ctrl:1
	s_cmp_lg_u32 s36, 0
	s_cbranch_scc1 .Ldq_bias_14
.Ldq_biasret_15:
	v_add_f32_e32 v58, 0x41000000, v56
	v_cmp_gt_f32_e32 vcc, v212, v58
	s_cbranch_vccnz .Ldq_resc_16
.Ldq_rescret_17:
	v_sub_f32_e32 v248, v212, v56
	v_exp_f32_e32 v249, v248
	s_nop 0
	v_add_f32_e32 v57, v249, v57
	s_nop 0
	v_mov_b32_e32 v196, v68
	v_mov_b32_e32 v197, v69
	v_mov_b32_e32 v198, v70
	v_mov_b32_e32 v199, v71
	v_mov_b32_dpp v220, v249 quad_perm:[0,0,0,0] row_mask:0xf bank_mask:0xf bound_ctrl:1
	v_mov_b32_dpp v222, v249 quad_perm:[1,1,1,1] row_mask:0xf bank_mask:0xf bound_ctrl:1
	v_mov_b32_dpp v224, v249 quad_perm:[2,2,2,2] row_mask:0xf bank_mask:0xf bound_ctrl:1
	v_mov_b32_dpp v226, v249 quad_perm:[3,3,3,3] row_mask:0xf bank_mask:0xf bound_ctrl:1
	v_permlane16_swap_b32_e32 v68, v196
	v_permlane16_swap_b32_e32 v69, v197
	v_permlane16_swap_b32_e32 v70, v198
	v_permlane16_swap_b32_e32 v71, v199
	v_pk_fma_f32 v[8:9], v[68:69], v[220:221], v[8:9] op_sel_hi:[1,0,1]
	v_pk_fma_f32 v[10:11], v[70:71], v[220:221], v[10:11] op_sel_hi:[1,0,1]
	v_pk_fma_f32 v[12:13], v[196:197], v[220:221], v[12:13] op_sel_hi:[1,0,1]
	v_pk_fma_f32 v[14:15], v[198:199], v[220:221], v[14:15] op_sel_hi:[1,0,1]
	v_pk_fma_f32 v[16:17], v[68:69], v[222:223], v[16:17] op_sel_hi:[1,0,1]
	v_pk_fma_f32 v[18:19], v[70:71], v[222:223], v[18:19] op_sel_hi:[1,0,1]
	v_pk_fma_f32 v[20:21], v[196:197], v[222:223], v[20:21] op_sel_hi:[1,0,1]
	v_pk_fma_f32 v[22:23], v[198:199], v[222:223], v[22:23] op_sel_hi:[1,0,1]
	v_pk_fma_f32 v[24:25], v[68:69], v[224:225], v[24:25] op_sel_hi:[1,0,1]
	v_pk_fma_f32 v[26:27], v[70:71], v[224:225], v[26:27] op_sel_hi:[1,0,1]
	v_pk_fma_f32 v[28:29], v[196:197], v[224:225], v[28:29] op_sel_hi:[1,0,1]
	v_pk_fma_f32 v[30:31], v[198:199], v[224:225], v[30:31] op_sel_hi:[1,0,1]
	v_pk_fma_f32 v[32:33], v[68:69], v[226:227], v[32:33] op_sel_hi:[1,0,1]
	v_pk_fma_f32 v[34:35], v[70:71], v[226:227], v[34:35] op_sel_hi:[1,0,1]
	v_pk_fma_f32 v[36:37], v[196:197], v[226:227], v[36:37] op_sel_hi:[1,0,1]
	v_pk_fma_f32 v[38:39], v[198:199], v[226:227], v[38:39] op_sel_hi:[1,0,1]
	v_add_f32_e32 v58, 0x41000000, v56
	v_cmp_gt_f32_e32 vcc, v216, v58
	s_cbranch_vccnz .Ldq_resc_18
.Ldq_rescret_19:
	v_sub_f32_e32 v248, v216, v56
	v_exp_f32_e32 v249, v248
	s_waitcnt vmcnt(20)
	v_add_f32_e32 v57, v249, v57
	s_nop 0
	v_mov_b32_e32 v200, v76
	v_mov_b32_e32 v201, v77
	v_mov_b32_e32 v202, v78
	v_mov_b32_e32 v203, v79
	v_mov_b32_dpp v230, v249 quad_perm:[0,0,0,0] row_mask:0xf bank_mask:0xf bound_ctrl:1
	v_mov_b32_dpp v232, v249 quad_perm:[1,1,1,1] row_mask:0xf bank_mask:0xf bound_ctrl:1
	v_mov_b32_dpp v234, v249 quad_perm:[2,2,2,2] row_mask:0xf bank_mask:0xf bound_ctrl:1
	v_mov_b32_dpp v236, v249 quad_perm:[3,3,3,3] row_mask:0xf bank_mask:0xf bound_ctrl:1
	v_permlane16_swap_b32_e32 v76, v200
	v_permlane16_swap_b32_e32 v77, v201
	v_permlane16_swap_b32_e32 v78, v202
	v_permlane16_swap_b32_e32 v79, v203
	v_pk_fma_f32 v[8:9], v[76:77], v[230:231], v[8:9] op_sel_hi:[1,0,1]
	v_pk_fma_f32 v[10:11], v[78:79], v[230:231], v[10:11] op_sel_hi:[1,0,1]
	v_pk_fma_f32 v[12:13], v[200:201], v[230:231], v[12:13] op_sel_hi:[1,0,1]
	v_pk_fma_f32 v[14:15], v[202:203], v[230:231], v[14:15] op_sel_hi:[1,0,1]
	v_pk_fma_f32 v[16:17], v[76:77], v[232:233], v[16:17] op_sel_hi:[1,0,1]
	v_pk_fma_f32 v[18:19], v[78:79], v[232:233], v[18:19] op_sel_hi:[1,0,1]
	v_pk_fma_f32 v[20:21], v[200:201], v[232:233], v[20:21] op_sel_hi:[1,0,1]
	v_pk_fma_f32 v[22:23], v[202:203], v[232:233], v[22:23] op_sel_hi:[1,0,1]
	v_pk_fma_f32 v[24:25], v[76:77], v[234:235], v[24:25] op_sel_hi:[1,0,1]
	v_pk_fma_f32 v[26:27], v[78:79], v[234:235], v[26:27] op_sel_hi:[1,0,1]
	v_pk_fma_f32 v[28:29], v[200:201], v[234:235], v[28:29] op_sel_hi:[1,0,1]
	v_pk_fma_f32 v[30:31], v[202:203], v[234:235], v[30:31] op_sel_hi:[1,0,1]
	v_pk_fma_f32 v[32:33], v[76:77], v[236:237], v[32:33] op_sel_hi:[1,0,1]
	v_pk_fma_f32 v[34:35], v[78:79], v[236:237], v[34:35] op_sel_hi:[1,0,1]
	v_pk_fma_f32 v[36:37], v[200:201], v[236:237], v[36:37] op_sel_hi:[1,0,1]
	v_pk_fma_f32 v[38:39], v[202:203], v[236:237], v[38:39] op_sel_hi:[1,0,1]
	s_add_i32 s23, s23, 1
	s_and_b32 s33, s23, 15
	s_cmp_eq_u32 s33, 0
	s_cbranch_scc1 .Ldq_np_20
	s_add_u32 s4, s4, 0x2000
	s_addc_u32 s5, s5, 0
	s_add_u32 s6, s6, 0x2000
	s_addc_u32 s7, s7, 0
.Ldq_npret_21:
	global_load_dwordx4 v[64:67], v59, s[4:5] offset:-4096 nt
	global_load_dwordx4 v[68:71], v59, s[6:7] offset:-4096 nt
	global_load_dwordx4 v[72:75], v59, s[4:5] nt
	global_load_dwordx4 v[76:79], v59, s[6:7] nt
	s_add_i32 s39, s39, 1
	s_lshr_b32 s33, s39, 4
	s_cmp_eq_u32 s33, 7
	s_cselect_b32 s36, s37, 0
	s_waitcnt vmcnt(21)
	v_mul_f32_e32 v212, v40, v80
	v_mul_f32_e32 v213, v44, v80
	v_mul_f32_e32 v214, v48, v80
	v_mul_f32_e32 v215, v52, v80
	v_mul_f32_e32 v216, v40, v88
	v_mul_f32_e32 v217, v44, v88
	v_mul_f32_e32 v218, v48, v88
	v_mul_f32_e32 v219, v52, v88
	v_fmac_f32_e32 v212, v81, v41
	v_fmac_f32_e32 v213, v81, v45
	v_fmac_f32_e32 v214, v81, v49
	v_fmac_f32_e32 v215, v81, v53
	v_fmac_f32_e32 v216, v89, v41
	v_fmac_f32_e32 v217, v89, v45
	v_fmac_f32_e32 v218, v89, v49
	v_fmac_f32_e32 v219, v89, v53
	v_fmac_f32_e32 v212, v82, v42
	v_fmac_f32_e32 v213, v82, v46
	v_fmac_f32_e32 v214, v82, v50
	v_fmac_f32_e32 v215, v82, v54
	v_fmac_f32_e32 v216, v90, v42
	v_fmac_f32_e32 v217, v90, v46
	v_fmac_f32_e32 v218, v90, v50
	v_fmac_f32_e32 v219, v90, v54
	v_fmac_f32_e32 v212, v83, v43
	v_fmac_f32_e32 v213, v83, v47
	v_fmac_f32_e32 v214, v83, v51
	v_fmac_f32_e32 v215, v83, v55
	v_fmac_f32_e32 v216, v91, v43
	v_fmac_f32_e32 v217, v91, v47
	v_fmac_f32_e32 v218, v91, v51
	v_fmac_f32_e32 v219, v91, v55
	v_cndmask_b32_e64 v241, v212, v213, s[8:9]
	v_cndmask_b32_e64 v245, v216, v217, s[8:9]
	v_cndmask_b32_e64 v243, v214, v215, s[8:9]
	v_cndmask_b32_e64 v247, v218, v219, s[8:9]
	v_cndmask_b32_e64 v240, v213, v212, s[8:9]
	v_cndmask_b32_e64 v244, v217, v216, s[8:9]
	v_cndmask_b32_e64 v242, v215, v214, s[8:9]
	v_cndmask_b32_e64 v246, v219, v218, s[8:9]
	v_add_f32_dpp v240, v241, v240 quad_perm:[1,0,3,2] row_mask:0xf bank_mask:0xf bound_ctrl:1
	v_add_f32_dpp v244, v245, v244 quad_perm:[1,0,3,2] row_mask:0xf bank_mask:0xf bound_ctrl:1
	v_add_f32_dpp v242, v243, v242 quad_perm:[1,0,3,2] row_mask:0xf bank_mask:0xf bound_ctrl:1
	v_add_f32_dpp v246, v247, v246 quad_perm:[1,0,3,2] row_mask:0xf bank_mask:0xf bound_ctrl:1
	v_cndmask_b32_e64 v213, v240, v242, s[34:35]
	v_cndmask_b32_e64 v217, v244, v246, s[34:35]
	v_cndmask_b32_e64 v212, v242, v240, s[34:35]
	v_cndmask_b32_e64 v216, v246, v244, s[34:35]
	s_nop 0
	v_add_f32_dpp v212, v213, v212 quad_perm:[2,3,0,1] row_mask:0xf bank_mask:0xf bound_ctrl:1
	v_add_f32_dpp v216, v217, v216 quad_perm:[2,3,0,1] row_mask:0xf bank_mask:0xf bound_ctrl:1
	s_nop 0
	v_add_f32_dpp v212, v212, v212 row_ror:4 row_mask:0xf bank_mask:0xf bound_ctrl:1
	v_add_f32_dpp v216, v216, v216 row_ror:4 row_mask:0xf bank_mask:0xf bound_ctrl:1
	s_nop 0
	v_add_f32_dpp v212, v212, v212 row_ror:8 row_mask:0xf bank_mask:0xf bound_ctrl:1
	v_add_f32_dpp v216, v216, v216 row_ror:8 row_mask:0xf bank_mask:0xf bound_ctrl:1
	s_cmp_lg_u32 s36, 0
	s_cbranch_scc1 .Ldq_bias_22

.Ldq_rescret_25:
	v_sub_f32_e32 v248, v212, v56
	v_exp_f32_e32 v249, v248
	s_nop 0
	v_add_f32_e32 v57, v249, v57
	s_nop 0
	v_mov_b32_e32 v196, v84
	v_mov_b32_e32 v197, v85
	v_mov_b32_e32 v198, v86
	v_mov_b32_e32 v199, v87
	v_mov_b32_dpp v220, v249 quad_perm:[0,0,0,0] row_mask:0xf bank_mask:0xf bound_ctrl:1
	v_mov_b32_dpp v222, v249 quad_perm:[1,1,1,1] row_mask:0xf bank_mask:0xf bound_ctrl:1
	v_mov_b32_dpp v224, v249 quad_perm:[2,2,2,2] row_mask:0xf bank_mask:0xf bound_ctrl:1
	v_mov_b32_dpp v226, v249 quad_perm:[3,3,3,3] row_mask:0xf bank_mask:0xf bound_ctrl:1
	v_permlane16_swap_b32_e32 v84, v196
	v_permlane16_swap_b32_e32 v85, v197
	v_permlane16_swap_b32_e32 v86, v198
	v_permlane16_swap_b32_e32 v87, v199
	v_pk_fma_f32 v[8:9], v[84:85], v[220:221], v[8:9] op_sel_hi:[1,0,1]
	v_pk_fma_f32 v[10:11], v[86:87], v[220:221], v[10:11] op_sel_hi:[1,0,1]
	v_pk_fma_f32 v[12:13], v[196:197], v[220:221], v[12:13] op_sel_hi:[1,0,1]
	v_pk_fma_f32 v[14:15], v[198:199], v[220:221], v[14:15] op_sel_hi:[1,0,1]
	v_pk_fma_f32 v[16:17], v[84:85], v[222:223], v[16:17] op_sel_hi:[1,0,1]
	v_pk_fma_f32 v[18:19], v[86:87], v[222:223], v[18:19] op_sel_hi:[1,0,1]
	v_pk_fma_f32 v[20:21], v[196:197], v[222:223], v[20:21] op_sel_hi:[1,0,1]
	v_pk_fma_f32 v[22:23], v[198:199], v[222:223], v[22:23] op_sel_hi:[1,0,1]
	v_pk_fma_f32 v[24:25], v[84:85], v[224:225], v[24:25] op_sel_hi:[1,0,1]
	v_pk_fma_f32 v[26:27], v[86:87], v[224:225], v[26:27] op_sel_hi:[1,0,1]
	v_pk_fma_f32 v[28:29], v[196:197], v[224:225], v[28:29] op_sel_hi:[1,0,1]
	v_pk_fma_f32 v[30:31], v[198:199], v[224:225], v[30:31] op_sel_hi:[1,0,1]
	v_pk_fma_f32 v[32:33], v[84:85], v[226:227], v[32:33] op_sel_hi:[1,0,1]
	v_pk_fma_f32 v[34:35], v[86:87], v[226:227], v[34:35] op_sel_hi:[1,0,1]
	v_pk_fma_f32 v[36:37], v[196:197], v[226:227], v[36:37] op_sel_hi:[1,0,1]
	v_pk_fma_f32 v[38:39], v[198:199], v[226:227], v[38:39] op_sel_hi:[1,0,1]
	v_add_f32_e32 v58, 0x41000000, v56
	v_cmp_gt_f32_e32 vcc, v216, v58
	s_cbranch_vccnz .Ldq_resc_26
.Ldq_rescret_27:
	v_sub_f32_e32 v248, v216, v56
	v_exp_f32_e32 v249, v248
	s_waitcnt vmcnt(20)
	v_add_f32_e32 v57, v249, v57
	s_nop 0
	v_mov_b32_e32 v200, v92
	v_mov_b32_e32 v201, v93
	v_mov_b32_e32 v202, v94
	v_mov_b32_e32 v203, v95
	v_mov_b32_dpp v230, v249 quad_perm:[0,0,0,0] row_mask:0xf bank_mask:0xf bound_ctrl:1
	v_mov_b32_dpp v232, v249 quad_perm:[1,1,1,1] row_mask:0xf bank_mask:0xf bound_ctrl:1
	v_mov_b32_dpp v234, v249 quad_perm:[2,2,2,2] row_mask:0xf bank_mask:0xf bound_ctrl:1
	v_mov_b32_dpp v236, v249 quad_perm:[3,3,3,3] row_mask:0xf bank_mask:0xf bound_ctrl:1
	v_permlane16_swap_b32_e32 v92, v200
	v_permlane16_swap_b32_e32 v93, v201
	v_permlane16_swap_b32_e32 v94, v202
	v_permlane16_swap_b32_e32 v95, v203
	v_pk_fma_f32 v[8:9], v[92:93], v[230:231], v[8:9] op_sel_hi:[1,0,1]
	v_pk_fma_f32 v[10:11], v[94:95], v[230:231], v[10:11] op_sel_hi:[1,0,1]
	v_pk_fma_f32 v[12:13], v[200:201], v[230:231], v[12:13] op_sel_hi:[1,0,1]
	v_pk_fma_f32 v[14:15], v[202:203], v[230:231], v[14:15] op_sel_hi:[1,0,1]
	v_pk_fma_f32 v[16:17], v[92:93], v[232:233], v[16:17] op_sel_hi:[1,0,1]
	v_pk_fma_f32 v[18:19], v[94:95], v[232:233], v[18:19] op_sel_hi:[1,0,1]
	v_pk_fma_f32 v[20:21], v[200:201], v[232:233], v[20:21] op_sel_hi:[1,0,1]
	v_pk_fma_f32 v[22:23], v[202:203], v[232:233], v[22:23] op_sel_hi:[1,0,1]
	v_pk_fma_f32 v[24:25], v[92:93], v[234:235], v[24:25] op_sel_hi:[1,0,1]
	v_pk_fma_f32 v[26:27], v[94:95], v[234:235], v[26:27] op_sel_hi:[1,0,1]
	v_pk_fma_f32 v[28:29], v[200:201], v[234:235], v[28:29] op_sel_hi:[1,0,1]
	v_pk_fma_f32 v[30:31], v[202:203], v[234:235], v[30:31] op_sel_hi:[1,0,1]
	v_pk_fma_f32 v[32:33], v[92:93], v[236:237], v[32:33] op_sel_hi:[1,0,1]
	v_pk_fma_f32 v[34:35], v[94:95], v[236:237], v[34:35] op_sel_hi:[1,0,1]
	v_pk_fma_f32 v[36:37], v[200:201], v[236:237], v[36:37] op_sel_hi:[1,0,1]
	v_pk_fma_f32 v[38:39], v[202:203], v[236:237], v[38:39] op_sel_hi:[1,0,1]
	s_add_i32 s23, s23, 1
	s_and_b32 s33, s23, 15
	s_cmp_eq_u32 s33, 0
	s_cbranch_scc1 .Ldq_np_28
	s_add_u32 s4, s4, 0x2000
	s_addc_u32 s5, s5, 0
	s_add_u32 s6, s6, 0x2000
	s_addc_u32 s7, s7, 0
.Ldq_npret_29:
	global_load_dwordx4 v[80:83], v59, s[4:5] offset:-4096 nt
	global_load_dwordx4 v[84:87], v59, s[6:7] offset:-4096 nt
	global_load_dwordx4 v[88:91], v59, s[4:5] nt
	global_load_dwordx4 v[92:95], v59, s[6:7] nt
	s_add_i32 s39, s39, 1
	s_lshr_b32 s33, s39, 4
	s_cmp_eq_u32 s33, 7
	s_cselect_b32 s36, s37, 0
	s_waitcnt vmcnt(21)
	v_mul_f32_e32 v212, v40, v96
	v_mul_f32_e32 v213, v44, v96
	v_mul_f32_e32 v214, v48, v96
	v_mul_f32_e32 v215, v52, v96
	v_mul_f32_e32 v216, v40, v104
	v_mul_f32_e32 v217, v44, v104
	v_mul_f32_e32 v218, v48, v104
	v_mul_f32_e32 v219, v52, v104
	v_fmac_f32_e32 v212, v97, v41
	v_fmac_f32_e32 v213, v97, v45
	v_fmac_f32_e32 v214, v97, v49
	v_fmac_f32_e32 v215, v97, v53
	v_fmac_f32_e32 v216, v105, v41
	v_fmac_f32_e32 v217, v105, v45
	v_fmac_f32_e32 v218, v105, v49
	v_fmac_f32_e32 v219, v105, v53
	v_fmac_f32_e32 v212, v98, v42
	v_fmac_f32_e32 v213, v98, v46
	v_fmac_f32_e32 v214, v98, v50
	v_fmac_f32_e32 v215, v98, v54
	v_fmac_f32_e32 v216, v106, v42
	v_fmac_f32_e32 v217, v106, v46
	v_fmac_f32_e32 v218, v106, v50
	v_fmac_f32_e32 v219, v106, v54
	v_fmac_f32_e32 v212, v99, v43
	v_fmac_f32_e32 v213, v99, v47
	v_fmac_f32_e32 v214, v99, v51
	v_fmac_f32_e32 v215, v99, v55
	v_fmac_f32_e32 v216, v107, v43
	v_fmac_f32_e32 v217, v107, v47
	v_fmac_f32_e32 v218, v107, v51
	v_fmac_f32_e32 v219, v107, v55
	v_cndmask_b32_e64 v241, v212, v213, s[8:9]
	v_cndmask_b32_e64 v245, v216, v217, s[8:9]
	v_cndmask_b32_e64 v243, v214, v215, s[8:9]
	v_cndmask_b32_e64 v247, v218, v219, s[8:9]
	v_cndmask_b32_e64 v240, v213, v212, s[8:9]
	v_cndmask_b32_e64 v244, v217, v216, s[8:9]
	v_cndmask_b32_e64 v242, v215, v214, s[8:9]
	v_cndmask_b32_e64 v246, v219, v218, s[8:9]
	v_add_f32_dpp v240, v241, v240 quad_perm:[1,0,3,2] row_mask:0xf bank_mask:0xf bound_ctrl:1
	v_add_f32_dpp v244, v245, v244 quad_perm:[1,0,3,2] row_mask:0xf bank_mask:0xf bound_ctrl:1
	v_add_f32_dpp v242, v243, v242 quad_perm:[1,0,3,2] row_mask:0xf bank_mask:0xf bound_ctrl:1
	v_add_f32_dpp v246, v247, v246 quad_perm:[1,0,3,2] row_mask:0xf bank_mask:0xf bound_ctrl:1
	v_cndmask_b32_e64 v213, v240, v242, s[34:35]
	v_cndmask_b32_e64 v217, v244, v246, s[34:35]
	v_cndmask_b32_e64 v212, v242, v240, s[34:35]
	v_cndmask_b32_e64 v216, v246, v244, s[34:35]
	s_nop 0
	v_add_f32_dpp v212, v213, v212 quad_perm:[2,3,0,1] row_mask:0xf bank_mask:0xf bound_ctrl:1
	v_add_f32_dpp v216, v217, v216 quad_perm:[2,3,0,1] row_mask:0xf bank_mask:0xf bound_ctrl:1
	s_nop 0
	v_add_f32_dpp v212, v212, v212 row_ror:4 row_mask:0xf bank_mask:0xf bound_ctrl:1
	v_add_f32_dpp v216, v216, v216 row_ror:4 row_mask:0xf bank_mask:0xf bound_ctrl:1
	s_nop 0
	v_add_f32_dpp v212, v212, v212 row_ror:8 row_mask:0xf bank_mask:0xf bound_ctrl:1
	v_add_f32_dpp v216, v216, v216 row_ror:8 row_mask:0xf bank_mask:0xf bound_ctrl:1
	s_cmp_lg_u32 s36, 0
	s_cbranch_scc1 .Ldq_bias_30

.Ldq_rescret_33:
	v_sub_f32_e32 v248, v212, v56
	v_exp_f32_e32 v249, v248
	s_nop 0
	v_add_f32_e32 v57, v249, v57
	s_nop 0
	v_mov_b32_e32 v196, v100
	v_mov_b32_e32 v197, v101
	v_mov_b32_e32 v198, v102
	v_mov_b32_e32 v199, v103
	v_mov_b32_dpp v220, v249 quad_perm:[0,0,0,0] row_mask:0xf bank_mask:0xf bound_ctrl:1
	v_mov_b32_dpp v222, v249 quad_perm:[1,1,1,1] row_mask:0xf bank_mask:0xf bound_ctrl:1
	v_mov_b32_dpp v224, v249 quad_perm:[2,2,2,2] row_mask:0xf bank_mask:0xf bound_ctrl:1
	v_mov_b32_dpp v226, v249 quad_perm:[3,3,3,3] row_mask:0xf bank_mask:0xf bound_ctrl:1
	v_permlane16_swap_b32_e32 v100, v196
	v_permlane16_swap_b32_e32 v101, v197
	v_permlane16_swap_b32_e32 v102, v198
	v_permlane16_swap_b32_e32 v103, v199
	v_pk_fma_f32 v[8:9], v[100:101], v[220:221], v[8:9] op_sel_hi:[1,0,1]
	v_pk_fma_f32 v[10:11], v[102:103], v[220:221], v[10:11] op_sel_hi:[1,0,1]
	v_pk_fma_f32 v[12:13], v[196:197], v[220:221], v[12:13] op_sel_hi:[1,0,1]
	v_pk_fma_f32 v[14:15], v[198:199], v[220:221], v[14:15] op_sel_hi:[1,0,1]
	v_pk_fma_f32 v[16:17], v[100:101], v[222:223], v[16:17] op_sel_hi:[1,0,1]
	v_pk_fma_f32 v[18:19], v[102:103], v[222:223], v[18:19] op_sel_hi:[1,0,1]
	v_pk_fma_f32 v[20:21], v[196:197], v[222:223], v[20:21] op_sel_hi:[1,0,1]
	v_pk_fma_f32 v[22:23], v[198:199], v[222:223], v[22:23] op_sel_hi:[1,0,1]
	v_pk_fma_f32 v[24:25], v[100:101], v[224:225], v[24:25] op_sel_hi:[1,0,1]
	v_pk_fma_f32 v[26:27], v[102:103], v[224:225], v[26:27] op_sel_hi:[1,0,1]
	v_pk_fma_f32 v[28:29], v[196:197], v[224:225], v[28:29] op_sel_hi:[1,0,1]
	v_pk_fma_f32 v[30:31], v[198:199], v[224:225], v[30:31] op_sel_hi:[1,0,1]
	v_pk_fma_f32 v[32:33], v[100:101], v[226:227], v[32:33] op_sel_hi:[1,0,1]
	v_pk_fma_f32 v[34:35], v[102:103], v[226:227], v[34:35] op_sel_hi:[1,0,1]
	v_pk_fma_f32 v[36:37], v[196:197], v[226:227], v[36:37] op_sel_hi:[1,0,1]
	v_pk_fma_f32 v[38:39], v[198:199], v[226:227], v[38:39] op_sel_hi:[1,0,1]
	v_add_f32_e32 v58, 0x41000000, v56
	v_cmp_gt_f32_e32 vcc, v216, v58
	s_cbranch_vccnz .Ldq_resc_34
.Ldq_rescret_35:
	v_sub_f32_e32 v248, v216, v56
	v_exp_f32_e32 v249, v248
	s_waitcnt vmcnt(20)
	v_add_f32_e32 v57, v249, v57
	s_nop 0
	v_mov_b32_e32 v200, v108
	v_mov_b32_e32 v201, v109
	v_mov_b32_e32 v202, v110
	v_mov_b32_e32 v203, v111
	v_mov_b32_dpp v230, v249 quad_perm:[0,0,0,0] row_mask:0xf bank_mask:0xf bound_ctrl:1
	v_mov_b32_dpp v232, v249 quad_perm:[1,1,1,1] row_mask:0xf bank_mask:0xf bound_ctrl:1
	v_mov_b32_dpp v234, v249 quad_perm:[2,2,2,2] row_mask:0xf bank_mask:0xf bound_ctrl:1
	v_mov_b32_dpp v236, v249 quad_perm:[3,3,3,3] row_mask:0xf bank_mask:0xf bound_ctrl:1
	v_permlane16_swap_b32_e32 v108, v200
	v_permlane16_swap_b32_e32 v109, v201
	v_permlane16_swap_b32_e32 v110, v202
	v_permlane16_swap_b32_e32 v111, v203
	v_pk_fma_f32 v[8:9], v[108:109], v[230:231], v[8:9] op_sel_hi:[1,0,1]
	v_pk_fma_f32 v[10:11], v[110:111], v[230:231], v[10:11] op_sel_hi:[1,0,1]
	v_pk_fma_f32 v[12:13], v[200:201], v[230:231], v[12:13] op_sel_hi:[1,0,1]
	v_pk_fma_f32 v[14:15], v[202:203], v[230:231], v[14:15] op_sel_hi:[1,0,1]
	v_pk_fma_f32 v[16:17], v[108:109], v[232:233], v[16:17] op_sel_hi:[1,0,1]
	v_pk_fma_f32 v[18:19], v[110:111], v[232:233], v[18:19] op_sel_hi:[1,0,1]
	v_pk_fma_f32 v[20:21], v[200:201], v[232:233], v[20:21] op_sel_hi:[1,0,1]
	v_pk_fma_f32 v[22:23], v[202:203], v[232:233], v[22:23] op_sel_hi:[1,0,1]
	v_pk_fma_f32 v[24:25], v[108:109], v[234:235], v[24:25] op_sel_hi:[1,0,1]
	v_pk_fma_f32 v[26:27], v[110:111], v[234:235], v[26:27] op_sel_hi:[1,0,1]
	v_pk_fma_f32 v[28:29], v[200:201], v[234:235], v[28:29] op_sel_hi:[1,0,1]
	v_pk_fma_f32 v[30:31], v[202:203], v[234:235], v[30:31] op_sel_hi:[1,0,1]
	v_pk_fma_f32 v[32:33], v[108:109], v[236:237], v[32:33] op_sel_hi:[1,0,1]
	v_pk_fma_f32 v[34:35], v[110:111], v[236:237], v[34:35] op_sel_hi:[1,0,1]
	v_pk_fma_f32 v[36:37], v[200:201], v[236:237], v[36:37] op_sel_hi:[1,0,1]
	v_pk_fma_f32 v[38:39], v[202:203], v[236:237], v[38:39] op_sel_hi:[1,0,1]
	s_add_i32 s23, s23, 1
	s_and_b32 s33, s23, 15
	s_cmp_eq_u32 s33, 0
	s_cbranch_scc1 .Ldq_np_36
	s_add_u32 s4, s4, 0x2000
	s_addc_u32 s5, s5, 0
	s_add_u32 s6, s6, 0x2000
	s_addc_u32 s7, s7, 0
.Ldq_npret_37:
	global_load_dwordx4 v[96:99], v59, s[4:5] offset:-4096 nt
	global_load_dwordx4 v[100:103], v59, s[6:7] offset:-4096 nt
	global_load_dwordx4 v[104:107], v59, s[4:5] nt
	global_load_dwordx4 v[108:111], v59, s[6:7] nt
	s_add_i32 s39, s39, 1
	s_lshr_b32 s33, s39, 4
	s_cmp_eq_u32 s33, 7
	s_cselect_b32 s36, s37, 0
	s_waitcnt vmcnt(21)
	v_mul_f32_e32 v212, v40, v112
	v_mul_f32_e32 v213, v44, v112
	v_mul_f32_e32 v214, v48, v112
	v_mul_f32_e32 v215, v52, v112
	v_mul_f32_e32 v216, v40, v120
	v_mul_f32_e32 v217, v44, v120
	v_mul_f32_e32 v218, v48, v120
	v_mul_f32_e32 v219, v52, v120
	v_fmac_f32_e32 v212, v113, v41
	v_fmac_f32_e32 v213, v113, v45
	v_fmac_f32_e32 v214, v113, v49
	v_fmac_f32_e32 v215, v113, v53
	v_fmac_f32_e32 v216, v121, v41
	v_fmac_f32_e32 v217, v121, v45
	v_fmac_f32_e32 v218, v121, v49
	v_fmac_f32_e32 v219, v121, v53
	v_fmac_f32_e32 v212, v114, v42
	v_fmac_f32_e32 v213, v114, v46
	v_fmac_f32_e32 v214, v114, v50
	v_fmac_f32_e32 v215, v114, v54
	v_fmac_f32_e32 v216, v122, v42
	v_fmac_f32_e32 v217, v122, v46
	v_fmac_f32_e32 v218, v122, v50
	v_fmac_f32_e32 v219, v122, v54
	v_fmac_f32_e32 v212, v115, v43
	v_fmac_f32_e32 v213, v115, v47
	v_fmac_f32_e32 v214, v115, v51
	v_fmac_f32_e32 v215, v115, v55
	v_fmac_f32_e32 v216, v123, v43
	v_fmac_f32_e32 v217, v123, v47
	v_fmac_f32_e32 v218, v123, v51
	v_fmac_f32_e32 v219, v123, v55
	v_cndmask_b32_e64 v241, v212, v213, s[8:9]
	v_cndmask_b32_e64 v245, v216, v217, s[8:9]
	v_cndmask_b32_e64 v243, v214, v215, s[8:9]
	v_cndmask_b32_e64 v247, v218, v219, s[8:9]
	v_cndmask_b32_e64 v240, v213, v212, s[8:9]
	v_cndmask_b32_e64 v244, v217, v216, s[8:9]
	v_cndmask_b32_e64 v242, v215, v214, s[8:9]
	v_cndmask_b32_e64 v246, v219, v218, s[8:9]
	v_add_f32_dpp v240, v241, v240 quad_perm:[1,0,3,2] row_mask:0xf bank_mask:0xf bound_ctrl:1
	v_add_f32_dpp v244, v245, v244 quad_perm:[1,0,3,2] row_mask:0xf bank_mask:0xf bound_ctrl:1
	v_add_f32_dpp v242, v243, v242 quad_perm:[1,0,3,2] row_mask:0xf bank_mask:0xf bound_ctrl:1
	v_add_f32_dpp v246, v247, v246 quad_perm:[1,0,3,2] row_mask:0xf bank_mask:0xf bound_ctrl:1
	v_cndmask_b32_e64 v213, v240, v242, s[34:35]
	v_cndmask_b32_e64 v217, v244, v246, s[34:35]
	v_cndmask_b32_e64 v212, v242, v240, s[34:35]
	v_cndmask_b32_e64 v216, v246, v244, s[34:35]
	s_nop 0
	v_add_f32_dpp v212, v213, v212 quad_perm:[2,3,0,1] row_mask:0xf bank_mask:0xf bound_ctrl:1
	v_add_f32_dpp v216, v217, v216 quad_perm:[2,3,0,1] row_mask:0xf bank_mask:0xf bound_ctrl:1
	s_nop 0
	v_add_f32_dpp v212, v212, v212 row_ror:4 row_mask:0xf bank_mask:0xf bound_ctrl:1
	v_add_f32_dpp v216, v216, v216 row_ror:4 row_mask:0xf bank_mask:0xf bound_ctrl:1
	s_nop 0
	v_add_f32_dpp v212, v212, v212 row_ror:8 row_mask:0xf bank_mask:0xf bound_ctrl:1
	v_add_f32_dpp v216, v216, v216 row_ror:8 row_mask:0xf bank_mask:0xf bound_ctrl:1
	s_cmp_lg_u32 s36, 0
	s_cbranch_scc1 .Ldq_bias_38

.Ldq_rescret_41:
	v_sub_f32_e32 v248, v212, v56
	v_exp_f32_e32 v249, v248
	s_nop 0
	v_add_f32_e32 v57, v249, v57
	s_nop 0
	v_mov_b32_e32 v196, v116
	v_mov_b32_e32 v197, v117
	v_mov_b32_e32 v198, v118
	v_mov_b32_e32 v199, v119
	v_mov_b32_dpp v220, v249 quad_perm:[0,0,0,0] row_mask:0xf bank_mask:0xf bound_ctrl:1
	v_mov_b32_dpp v222, v249 quad_perm:[1,1,1,1] row_mask:0xf bank_mask:0xf bound_ctrl:1
	v_mov_b32_dpp v224, v249 quad_perm:[2,2,2,2] row_mask:0xf bank_mask:0xf bound_ctrl:1
	v_mov_b32_dpp v226, v249 quad_perm:[3,3,3,3] row_mask:0xf bank_mask:0xf bound_ctrl:1
	v_permlane16_swap_b32_e32 v116, v196
	v_permlane16_swap_b32_e32 v117, v197
	v_permlane16_swap_b32_e32 v118, v198
	v_permlane16_swap_b32_e32 v119, v199
	v_pk_fma_f32 v[8:9], v[116:117], v[220:221], v[8:9] op_sel_hi:[1,0,1]
	v_pk_fma_f32 v[10:11], v[118:119], v[220:221], v[10:11] op_sel_hi:[1,0,1]
	v_pk_fma_f32 v[12:13], v[196:197], v[220:221], v[12:13] op_sel_hi:[1,0,1]
	v_pk_fma_f32 v[14:15], v[198:199], v[220:221], v[14:15] op_sel_hi:[1,0,1]
	v_pk_fma_f32 v[16:17], v[116:117], v[222:223], v[16:17] op_sel_hi:[1,0,1]
	v_pk_fma_f32 v[18:19], v[118:119], v[222:223], v[18:19] op_sel_hi:[1,0,1]
	v_pk_fma_f32 v[20:21], v[196:197], v[222:223], v[20:21] op_sel_hi:[1,0,1]
	v_pk_fma_f32 v[22:23], v[198:199], v[222:223], v[22:23] op_sel_hi:[1,0,1]
	v_pk_fma_f32 v[24:25], v[116:117], v[224:225], v[24:25] op_sel_hi:[1,0,1]
	v_pk_fma_f32 v[26:27], v[118:119], v[224:225], v[26:27] op_sel_hi:[1,0,1]
	v_pk_fma_f32 v[28:29], v[196:197], v[224:225], v[28:29] op_sel_hi:[1,0,1]
	v_pk_fma_f32 v[30:31], v[198:199], v[224:225], v[30:31] op_sel_hi:[1,0,1]
	v_pk_fma_f32 v[32:33], v[116:117], v[226:227], v[32:33] op_sel_hi:[1,0,1]
	v_pk_fma_f32 v[34:35], v[118:119], v[226:227], v[34:35] op_sel_hi:[1,0,1]
	v_pk_fma_f32 v[36:37], v[196:197], v[226:227], v[36:37] op_sel_hi:[1,0,1]
	v_pk_fma_f32 v[38:39], v[198:199], v[226:227], v[38:39] op_sel_hi:[1,0,1]
	v_add_f32_e32 v58, 0x41000000, v56
	v_cmp_gt_f32_e32 vcc, v216, v58
	s_cbranch_vccnz .Ldq_resc_42
.Ldq_rescret_43:
	v_sub_f32_e32 v248, v216, v56
	v_exp_f32_e32 v249, v248
	s_waitcnt vmcnt(20)
	v_add_f32_e32 v57, v249, v57
	s_nop 0
	v_mov_b32_e32 v200, v124
	v_mov_b32_e32 v201, v125
	v_mov_b32_e32 v202, v126
	v_mov_b32_e32 v203, v127
	v_mov_b32_dpp v230, v249 quad_perm:[0,0,0,0] row_mask:0xf bank_mask:0xf bound_ctrl:1
	v_mov_b32_dpp v232, v249 quad_perm:[1,1,1,1] row_mask:0xf bank_mask:0xf bound_ctrl:1
	v_mov_b32_dpp v234, v249 quad_perm:[2,2,2,2] row_mask:0xf bank_mask:0xf bound_ctrl:1
	v_mov_b32_dpp v236, v249 quad_perm:[3,3,3,3] row_mask:0xf bank_mask:0xf bound_ctrl:1
	v_permlane16_swap_b32_e32 v124, v200
	v_permlane16_swap_b32_e32 v125, v201
	v_permlane16_swap_b32_e32 v126, v202
	v_permlane16_swap_b32_e32 v127, v203
	v_pk_fma_f32 v[8:9], v[124:125], v[230:231], v[8:9] op_sel_hi:[1,0,1]
	v_pk_fma_f32 v[10:11], v[126:127], v[230:231], v[10:11] op_sel_hi:[1,0,1]
	v_pk_fma_f32 v[12:13], v[200:201], v[230:231], v[12:13] op_sel_hi:[1,0,1]
	v_pk_fma_f32 v[14:15], v[202:203], v[230:231], v[14:15] op_sel_hi:[1,0,1]
	v_pk_fma_f32 v[16:17], v[124:125], v[232:233], v[16:17] op_sel_hi:[1,0,1]
	v_pk_fma_f32 v[18:19], v[126:127], v[232:233], v[18:19] op_sel_hi:[1,0,1]
	v_pk_fma_f32 v[20:21], v[200:201], v[232:233], v[20:21] op_sel_hi:[1,0,1]
	v_pk_fma_f32 v[22:23], v[202:203], v[232:233], v[22:23] op_sel_hi:[1,0,1]
	v_pk_fma_f32 v[24:25], v[124:125], v[234:235], v[24:25] op_sel_hi:[1,0,1]
	v_pk_fma_f32 v[26:27], v[126:127], v[234:235], v[26:27] op_sel_hi:[1,0,1]
	v_pk_fma_f32 v[28:29], v[200:201], v[234:235], v[28:29] op_sel_hi:[1,0,1]
	v_pk_fma_f32 v[30:31], v[202:203], v[234:235], v[30:31] op_sel_hi:[1,0,1]
	v_pk_fma_f32 v[32:33], v[124:125], v[236:237], v[32:33] op_sel_hi:[1,0,1]
	v_pk_fma_f32 v[34:35], v[126:127], v[236:237], v[34:35] op_sel_hi:[1,0,1]
	v_pk_fma_f32 v[36:37], v[200:201], v[236:237], v[36:37] op_sel_hi:[1,0,1]
	v_pk_fma_f32 v[38:39], v[202:203], v[236:237], v[38:39] op_sel_hi:[1,0,1]
	s_add_i32 s23, s23, 1
	s_and_b32 s33, s23, 15
	s_cmp_eq_u32 s33, 0
	s_cbranch_scc1 .Ldq_np_44
	s_add_u32 s4, s4, 0x2000
	s_addc_u32 s5, s5, 0
	s_add_u32 s6, s6, 0x2000
	s_addc_u32 s7, s7, 0
.Ldq_npret_45:
	global_load_dwordx4 v[112:115], v59, s[4:5] offset:-4096 nt
	global_load_dwordx4 v[116:119], v59, s[6:7] offset:-4096 nt
	global_load_dwordx4 v[120:123], v59, s[4:5] nt
	global_load_dwordx4 v[124:127], v59, s[6:7] nt
	s_add_i32 s39, s39, 1
	s_lshr_b32 s33, s39, 4
	s_cmp_eq_u32 s33, 7
	s_cselect_b32 s36, s37, 0
	s_waitcnt vmcnt(21)
	v_mul_f32_e32 v212, v40, v128
	v_mul_f32_e32 v213, v44, v128
	v_mul_f32_e32 v214, v48, v128
	v_mul_f32_e32 v215, v52, v128
	v_mul_f32_e32 v216, v40, v136
	v_mul_f32_e32 v217, v44, v136
	v_mul_f32_e32 v218, v48, v136
	v_mul_f32_e32 v219, v52, v136
	v_fmac_f32_e32 v212, v129, v41
	v_fmac_f32_e32 v213, v129, v45
	v_fmac_f32_e32 v214, v129, v49
	v_fmac_f32_e32 v215, v129, v53
	v_fmac_f32_e32 v216, v137, v41
	v_fmac_f32_e32 v217, v137, v45
	v_fmac_f32_e32 v218, v137, v49
	v_fmac_f32_e32 v219, v137, v53
	v_fmac_f32_e32 v212, v130, v42
	v_fmac_f32_e32 v213, v130, v46
	v_fmac_f32_e32 v214, v130, v50
	v_fmac_f32_e32 v215, v130, v54
	v_fmac_f32_e32 v216, v138, v42
	v_fmac_f32_e32 v217, v138, v46
	v_fmac_f32_e32 v218, v138, v50
	v_fmac_f32_e32 v219, v138, v54
	v_fmac_f32_e32 v212, v131, v43
	v_fmac_f32_e32 v213, v131, v47
	v_fmac_f32_e32 v214, v131, v51
	v_fmac_f32_e32 v215, v131, v55
	v_fmac_f32_e32 v216, v139, v43
	v_fmac_f32_e32 v217, v139, v47
	v_fmac_f32_e32 v218, v139, v51
	v_fmac_f32_e32 v219, v139, v55
	v_cndmask_b32_e64 v241, v212, v213, s[8:9]
	v_cndmask_b32_e64 v245, v216, v217, s[8:9]
	v_cndmask_b32_e64 v243, v214, v215, s[8:9]
	v_cndmask_b32_e64 v247, v218, v219, s[8:9]
	v_cndmask_b32_e64 v240, v213, v212, s[8:9]
	v_cndmask_b32_e64 v244, v217, v216, s[8:9]
	v_cndmask_b32_e64 v242, v215, v214, s[8:9]
	v_cndmask_b32_e64 v246, v219, v218, s[8:9]
	v_add_f32_dpp v240, v241, v240 quad_perm:[1,0,3,2] row_mask:0xf bank_mask:0xf bound_ctrl:1
	v_add_f32_dpp v244, v245, v244 quad_perm:[1,0,3,2] row_mask:0xf bank_mask:0xf bound_ctrl:1
	v_add_f32_dpp v242, v243, v242 quad_perm:[1,0,3,2] row_mask:0xf bank_mask:0xf bound_ctrl:1
	v_add_f32_dpp v246, v247, v246 quad_perm:[1,0,3,2] row_mask:0xf bank_mask:0xf bound_ctrl:1
	v_cndmask_b32_e64 v213, v240, v242, s[34:35]
	v_cndmask_b32_e64 v217, v244, v246, s[34:35]
	v_cndmask_b32_e64 v212, v242, v240, s[34:35]
	v_cndmask_b32_e64 v216, v246, v244, s[34:35]
	s_nop 0
	v_add_f32_dpp v212, v213, v212 quad_perm:[2,3,0,1] row_mask:0xf bank_mask:0xf bound_ctrl:1
	v_add_f32_dpp v216, v217, v216 quad_perm:[2,3,0,1] row_mask:0xf bank_mask:0xf bound_ctrl:1
	s_nop 0
	v_add_f32_dpp v212, v212, v212 row_ror:4 row_mask:0xf bank_mask:0xf bound_ctrl:1
	v_add_f32_dpp v216, v216, v216 row_ror:4 row_mask:0xf bank_mask:0xf bound_ctrl:1
	s_nop 0
	v_add_f32_dpp v212, v212, v212 row_ror:8 row_mask:0xf bank_mask:0xf bound_ctrl:1
	v_add_f32_dpp v216, v216, v216 row_ror:8 row_mask:0xf bank_mask:0xf bound_ctrl:1
	s_cmp_lg_u32 s36, 0
	s_cbranch_scc1 .Ldq_bias_46

.Ldq_rescret_49:
	v_sub_f32_e32 v248, v212, v56
	v_exp_f32_e32 v249, v248
	s_nop 0
	v_add_f32_e32 v57, v249, v57
	s_nop 0
	v_mov_b32_e32 v196, v132
	v_mov_b32_e32 v197, v133
	v_mov_b32_e32 v198, v134
	v_mov_b32_e32 v199, v135
	v_mov_b32_dpp v220, v249 quad_perm:[0,0,0,0] row_mask:0xf bank_mask:0xf bound_ctrl:1
	v_mov_b32_dpp v222, v249 quad_perm:[1,1,1,1] row_mask:0xf bank_mask:0xf bound_ctrl:1
	v_mov_b32_dpp v224, v249 quad_perm:[2,2,2,2] row_mask:0xf bank_mask:0xf bound_ctrl:1
	v_mov_b32_dpp v226, v249 quad_perm:[3,3,3,3] row_mask:0xf bank_mask:0xf bound_ctrl:1
	v_permlane16_swap_b32_e32 v132, v196
	v_permlane16_swap_b32_e32 v133, v197
	v_permlane16_swap_b32_e32 v134, v198
	v_permlane16_swap_b32_e32 v135, v199
	v_pk_fma_f32 v[8:9], v[132:133], v[220:221], v[8:9] op_sel_hi:[1,0,1]
	v_pk_fma_f32 v[10:11], v[134:135], v[220:221], v[10:11] op_sel_hi:[1,0,1]
	v_pk_fma_f32 v[12:13], v[196:197], v[220:221], v[12:13] op_sel_hi:[1,0,1]
	v_pk_fma_f32 v[14:15], v[198:199], v[220:221], v[14:15] op_sel_hi:[1,0,1]
	v_pk_fma_f32 v[16:17], v[132:133], v[222:223], v[16:17] op_sel_hi:[1,0,1]
	v_pk_fma_f32 v[18:19], v[134:135], v[222:223], v[18:19] op_sel_hi:[1,0,1]
	v_pk_fma_f32 v[20:21], v[196:197], v[222:223], v[20:21] op_sel_hi:[1,0,1]
	v_pk_fma_f32 v[22:23], v[198:199], v[222:223], v[22:23] op_sel_hi:[1,0,1]
	v_pk_fma_f32 v[24:25], v[132:133], v[224:225], v[24:25] op_sel_hi:[1,0,1]
	v_pk_fma_f32 v[26:27], v[134:135], v[224:225], v[26:27] op_sel_hi:[1,0,1]
	v_pk_fma_f32 v[28:29], v[196:197], v[224:225], v[28:29] op_sel_hi:[1,0,1]
	v_pk_fma_f32 v[30:31], v[198:199], v[224:225], v[30:31] op_sel_hi:[1,0,1]
	v_pk_fma_f32 v[32:33], v[132:133], v[226:227], v[32:33] op_sel_hi:[1,0,1]
	v_pk_fma_f32 v[34:35], v[134:135], v[226:227], v[34:35] op_sel_hi:[1,0,1]
	v_pk_fma_f32 v[36:37], v[196:197], v[226:227], v[36:37] op_sel_hi:[1,0,1]
	v_pk_fma_f32 v[38:39], v[198:199], v[226:227], v[38:39] op_sel_hi:[1,0,1]
	v_add_f32_e32 v58, 0x41000000, v56
	v_cmp_gt_f32_e32 vcc, v216, v58
	s_cbranch_vccnz .Ldq_resc_50
.Ldq_rescret_51:
	v_sub_f32_e32 v248, v216, v56
	v_exp_f32_e32 v249, v248
	s_waitcnt vmcnt(20)
	v_add_f32_e32 v57, v249, v57
	s_nop 0
	v_mov_b32_e32 v200, v140
	v_mov_b32_e32 v201, v141
	v_mov_b32_e32 v202, v142
	v_mov_b32_e32 v203, v143
	v_mov_b32_dpp v230, v249 quad_perm:[0,0,0,0] row_mask:0xf bank_mask:0xf bound_ctrl:1
	v_mov_b32_dpp v232, v249 quad_perm:[1,1,1,1] row_mask:0xf bank_mask:0xf bound_ctrl:1
	v_mov_b32_dpp v234, v249 quad_perm:[2,2,2,2] row_mask:0xf bank_mask:0xf bound_ctrl:1
	v_mov_b32_dpp v236, v249 quad_perm:[3,3,3,3] row_mask:0xf bank_mask:0xf bound_ctrl:1
	v_permlane16_swap_b32_e32 v140, v200
	v_permlane16_swap_b32_e32 v141, v201
	v_permlane16_swap_b32_e32 v142, v202
	v_permlane16_swap_b32_e32 v143, v203
	v_pk_fma_f32 v[8:9], v[140:141], v[230:231], v[8:9] op_sel_hi:[1,0,1]
	v_pk_fma_f32 v[10:11], v[142:143], v[230:231], v[10:11] op_sel_hi:[1,0,1]
	v_pk_fma_f32 v[12:13], v[200:201], v[230:231], v[12:13] op_sel_hi:[1,0,1]
	v_pk_fma_f32 v[14:15], v[202:203], v[230:231], v[14:15] op_sel_hi:[1,0,1]
	v_pk_fma_f32 v[16:17], v[140:141], v[232:233], v[16:17] op_sel_hi:[1,0,1]
	v_pk_fma_f32 v[18:19], v[142:143], v[232:233], v[18:19] op_sel_hi:[1,0,1]
	v_pk_fma_f32 v[20:21], v[200:201], v[232:233], v[20:21] op_sel_hi:[1,0,1]
	v_pk_fma_f32 v[22:23], v[202:203], v[232:233], v[22:23] op_sel_hi:[1,0,1]
	v_pk_fma_f32 v[24:25], v[140:141], v[234:235], v[24:25] op_sel_hi:[1,0,1]
	v_pk_fma_f32 v[26:27], v[142:143], v[234:235], v[26:27] op_sel_hi:[1,0,1]
	v_pk_fma_f32 v[28:29], v[200:201], v[234:235], v[28:29] op_sel_hi:[1,0,1]
	v_pk_fma_f32 v[30:31], v[202:203], v[234:235], v[30:31] op_sel_hi:[1,0,1]
	v_pk_fma_f32 v[32:33], v[140:141], v[236:237], v[32:33] op_sel_hi:[1,0,1]
	v_pk_fma_f32 v[34:35], v[142:143], v[236:237], v[34:35] op_sel_hi:[1,0,1]
	v_pk_fma_f32 v[36:37], v[200:201], v[236:237], v[36:37] op_sel_hi:[1,0,1]
	v_pk_fma_f32 v[38:39], v[202:203], v[236:237], v[38:39] op_sel_hi:[1,0,1]
	s_add_i32 s23, s23, 1
	s_and_b32 s33, s23, 15
	s_cmp_eq_u32 s33, 0
	s_cbranch_scc1 .Ldq_np_52
	s_add_u32 s4, s4, 0x2000
	s_addc_u32 s5, s5, 0
	s_add_u32 s6, s6, 0x2000
	s_addc_u32 s7, s7, 0
.Ldq_npret_53:
	global_load_dwordx4 v[128:131], v59, s[4:5] offset:-4096 nt
	global_load_dwordx4 v[132:135], v59, s[6:7] offset:-4096 nt
	global_load_dwordx4 v[136:139], v59, s[4:5] nt
	global_load_dwordx4 v[140:143], v59, s[6:7] nt
	s_add_i32 s39, s39, 1
	s_lshr_b32 s33, s39, 4
	s_cmp_eq_u32 s33, 7
	s_cselect_b32 s36, s37, 0
	s_waitcnt vmcnt(21)
	v_mul_f32_e32 v212, v40, v144
	v_mul_f32_e32 v213, v44, v144
	v_mul_f32_e32 v214, v48, v144
	v_mul_f32_e32 v215, v52, v144
	v_mul_f32_e32 v216, v40, v152
	v_mul_f32_e32 v217, v44, v152
	v_mul_f32_e32 v218, v48, v152
	v_mul_f32_e32 v219, v52, v152
	v_fmac_f32_e32 v212, v145, v41
	v_fmac_f32_e32 v213, v145, v45
	v_fmac_f32_e32 v214, v145, v49
	v_fmac_f32_e32 v215, v145, v53
	v_fmac_f32_e32 v216, v153, v41
	v_fmac_f32_e32 v217, v153, v45
	v_fmac_f32_e32 v218, v153, v49
	v_fmac_f32_e32 v219, v153, v53
	v_fmac_f32_e32 v212, v146, v42
	v_fmac_f32_e32 v213, v146, v46
	v_fmac_f32_e32 v214, v146, v50
	v_fmac_f32_e32 v215, v146, v54
	v_fmac_f32_e32 v216, v154, v42
	v_fmac_f32_e32 v217, v154, v46
	v_fmac_f32_e32 v218, v154, v50
	v_fmac_f32_e32 v219, v154, v54
	v_fmac_f32_e32 v212, v147, v43
	v_fmac_f32_e32 v213, v147, v47
	v_fmac_f32_e32 v214, v147, v51
	v_fmac_f32_e32 v215, v147, v55
	v_fmac_f32_e32 v216, v155, v43
	v_fmac_f32_e32 v217, v155, v47
	v_fmac_f32_e32 v218, v155, v51
	v_fmac_f32_e32 v219, v155, v55
	v_cndmask_b32_e64 v241, v212, v213, s[8:9]
	v_cndmask_b32_e64 v245, v216, v217, s[8:9]
	v_cndmask_b32_e64 v243, v214, v215, s[8:9]
	v_cndmask_b32_e64 v247, v218, v219, s[8:9]
	v_cndmask_b32_e64 v240, v213, v212, s[8:9]
	v_cndmask_b32_e64 v244, v217, v216, s[8:9]
	v_cndmask_b32_e64 v242, v215, v214, s[8:9]
	v_cndmask_b32_e64 v246, v219, v218, s[8:9]
	v_add_f32_dpp v240, v241, v240 quad_perm:[1,0,3,2] row_mask:0xf bank_mask:0xf bound_ctrl:1
	v_add_f32_dpp v244, v245, v244 quad_perm:[1,0,3,2] row_mask:0xf bank_mask:0xf bound_ctrl:1
	v_add_f32_dpp v242, v243, v242 quad_perm:[1,0,3,2] row_mask:0xf bank_mask:0xf bound_ctrl:1
	v_add_f32_dpp v246, v247, v246 quad_perm:[1,0,3,2] row_mask:0xf bank_mask:0xf bound_ctrl:1
	v_cndmask_b32_e64 v213, v240, v242, s[34:35]
	v_cndmask_b32_e64 v217, v244, v246, s[34:35]
	v_cndmask_b32_e64 v212, v242, v240, s[34:35]
	v_cndmask_b32_e64 v216, v246, v244, s[34:35]
	s_nop 0
	v_add_f32_dpp v212, v213, v212 quad_perm:[2,3,0,1] row_mask:0xf bank_mask:0xf bound_ctrl:1
	v_add_f32_dpp v216, v217, v216 quad_perm:[2,3,0,1] row_mask:0xf bank_mask:0xf bound_ctrl:1
	s_nop 0
	v_add_f32_dpp v212, v212, v212 row_ror:4 row_mask:0xf bank_mask:0xf bound_ctrl:1
	v_add_f32_dpp v216, v216, v216 row_ror:4 row_mask:0xf bank_mask:0xf bound_ctrl:1
	s_nop 0
	v_add_f32_dpp v212, v212, v212 row_ror:8 row_mask:0xf bank_mask:0xf bound_ctrl:1
	v_add_f32_dpp v216, v216, v216 row_ror:8 row_mask:0xf bank_mask:0xf bound_ctrl:1
	s_cmp_lg_u32 s36, 0
	s_cbranch_scc1 .Ldq_bias_54

.Ldq_rescret_57:
	v_sub_f32_e32 v248, v212, v56
	v_exp_f32_e32 v249, v248
	s_nop 0
	v_add_f32_e32 v57, v249, v57
	s_nop 0
	v_mov_b32_e32 v196, v148
	v_mov_b32_e32 v197, v149
	v_mov_b32_e32 v198, v150
	v_mov_b32_e32 v199, v151
	v_mov_b32_dpp v220, v249 quad_perm:[0,0,0,0] row_mask:0xf bank_mask:0xf bound_ctrl:1
	v_mov_b32_dpp v222, v249 quad_perm:[1,1,1,1] row_mask:0xf bank_mask:0xf bound_ctrl:1
	v_mov_b32_dpp v224, v249 quad_perm:[2,2,2,2] row_mask:0xf bank_mask:0xf bound_ctrl:1
	v_mov_b32_dpp v226, v249 quad_perm:[3,3,3,3] row_mask:0xf bank_mask:0xf bound_ctrl:1
	v_permlane16_swap_b32_e32 v148, v196
	v_permlane16_swap_b32_e32 v149, v197
	v_permlane16_swap_b32_e32 v150, v198
	v_permlane16_swap_b32_e32 v151, v199
	v_pk_fma_f32 v[8:9], v[148:149], v[220:221], v[8:9] op_sel_hi:[1,0,1]
	v_pk_fma_f32 v[10:11], v[150:151], v[220:221], v[10:11] op_sel_hi:[1,0,1]
	v_pk_fma_f32 v[12:13], v[196:197], v[220:221], v[12:13] op_sel_hi:[1,0,1]
	v_pk_fma_f32 v[14:15], v[198:199], v[220:221], v[14:15] op_sel_hi:[1,0,1]
	v_pk_fma_f32 v[16:17], v[148:149], v[222:223], v[16:17] op_sel_hi:[1,0,1]
	v_pk_fma_f32 v[18:19], v[150:151], v[222:223], v[18:19] op_sel_hi:[1,0,1]
	v_pk_fma_f32 v[20:21], v[196:197], v[222:223], v[20:21] op_sel_hi:[1,0,1]
	v_pk_fma_f32 v[22:23], v[198:199], v[222:223], v[22:23] op_sel_hi:[1,0,1]
	v_pk_fma_f32 v[24:25], v[148:149], v[224:225], v[24:25] op_sel_hi:[1,0,1]
	v_pk_fma_f32 v[26:27], v[150:151], v[224:225], v[26:27] op_sel_hi:[1,0,1]
	v_pk_fma_f32 v[28:29], v[196:197], v[224:225], v[28:29] op_sel_hi:[1,0,1]
	v_pk_fma_f32 v[30:31], v[198:199], v[224:225], v[30:31] op_sel_hi:[1,0,1]
	v_pk_fma_f32 v[32:33], v[148:149], v[226:227], v[32:33] op_sel_hi:[1,0,1]
	v_pk_fma_f32 v[34:35], v[150:151], v[226:227], v[34:35] op_sel_hi:[1,0,1]
	v_pk_fma_f32 v[36:37], v[196:197], v[226:227], v[36:37] op_sel_hi:[1,0,1]
	v_pk_fma_f32 v[38:39], v[198:199], v[226:227], v[38:39] op_sel_hi:[1,0,1]
	v_add_f32_e32 v58, 0x41000000, v56
	v_cmp_gt_f32_e32 vcc, v216, v58
	s_cbranch_vccnz .Ldq_resc_58
.Ldq_rescret_59:
	v_sub_f32_e32 v248, v216, v56
	v_exp_f32_e32 v249, v248
	s_waitcnt vmcnt(20)
	v_add_f32_e32 v57, v249, v57
	s_nop 0
	v_mov_b32_e32 v200, v156
	v_mov_b32_e32 v201, v157
	v_mov_b32_e32 v202, v158
	v_mov_b32_e32 v203, v159
	v_mov_b32_dpp v230, v249 quad_perm:[0,0,0,0] row_mask:0xf bank_mask:0xf bound_ctrl:1
	v_mov_b32_dpp v232, v249 quad_perm:[1,1,1,1] row_mask:0xf bank_mask:0xf bound_ctrl:1
	v_mov_b32_dpp v234, v249 quad_perm:[2,2,2,2] row_mask:0xf bank_mask:0xf bound_ctrl:1
	v_mov_b32_dpp v236, v249 quad_perm:[3,3,3,3] row_mask:0xf bank_mask:0xf bound_ctrl:1
	v_permlane16_swap_b32_e32 v156, v200
	v_permlane16_swap_b32_e32 v157, v201
	v_permlane16_swap_b32_e32 v158, v202
	v_permlane16_swap_b32_e32 v159, v203
	v_pk_fma_f32 v[8:9], v[156:157], v[230:231], v[8:9] op_sel_hi:[1,0,1]
	v_pk_fma_f32 v[10:11], v[158:159], v[230:231], v[10:11] op_sel_hi:[1,0,1]
	v_pk_fma_f32 v[12:13], v[200:201], v[230:231], v[12:13] op_sel_hi:[1,0,1]
	v_pk_fma_f32 v[14:15], v[202:203], v[230:231], v[14:15] op_sel_hi:[1,0,1]
	v_pk_fma_f32 v[16:17], v[156:157], v[232:233], v[16:17] op_sel_hi:[1,0,1]
	v_pk_fma_f32 v[18:19], v[158:159], v[232:233], v[18:19] op_sel_hi:[1,0,1]
	v_pk_fma_f32 v[20:21], v[200:201], v[232:233], v[20:21] op_sel_hi:[1,0,1]
	v_pk_fma_f32 v[22:23], v[202:203], v[232:233], v[22:23] op_sel_hi:[1,0,1]
	v_pk_fma_f32 v[24:25], v[156:157], v[234:235], v[24:25] op_sel_hi:[1,0,1]
	v_pk_fma_f32 v[26:27], v[158:159], v[234:235], v[26:27] op_sel_hi:[1,0,1]
	v_pk_fma_f32 v[28:29], v[200:201], v[234:235], v[28:29] op_sel_hi:[1,0,1]
	v_pk_fma_f32 v[30:31], v[202:203], v[234:235], v[30:31] op_sel_hi:[1,0,1]
	v_pk_fma_f32 v[32:33], v[156:157], v[236:237], v[32:33] op_sel_hi:[1,0,1]
	v_pk_fma_f32 v[34:35], v[158:159], v[236:237], v[34:35] op_sel_hi:[1,0,1]
	v_pk_fma_f32 v[36:37], v[200:201], v[236:237], v[36:37] op_sel_hi:[1,0,1]
	v_pk_fma_f32 v[38:39], v[202:203], v[236:237], v[38:39] op_sel_hi:[1,0,1]
	s_add_i32 s56, s56, -1
	s_cmp_lg_u32 s56, 0
	s_cbranch_scc1 .Ldq_loop_11
	s_add_i32 s23, s23, 1
	s_and_b32 s33, s23, 15
	s_cmp_eq_u32 s33, 0
	s_cbranch_scc1 .Ldq_np_60
	s_add_u32 s4, s4, 0x2000
	s_addc_u32 s5, s5, 0
	s_add_u32 s6, s6, 0x2000
	s_addc_u32 s7, s7, 0

.Ldq_rescret_83:
	v_sub_f32_e32 v248, v216, v56
	v_exp_f32_e32 v249, v248
	s_waitcnt vmcnt(20)
	v_add_f32_e32 v57, v249, v57
	s_nop 0
	v_mov_b32_e32 v200, v108
	v_mov_b32_e32 v201, v109
	v_mov_b32_e32 v202, v110
	v_mov_b32_e32 v203, v111
	v_mov_b32_dpp v230, v249 quad_perm:[0,0,0,0] row_mask:0xf bank_mask:0xf bound_ctrl:1
	v_mov_b32_dpp v232, v249 quad_perm:[1,1,1,1] row_mask:0xf bank_mask:0xf bound_ctrl:1
	v_mov_b32_dpp v234, v249 quad_perm:[2,2,2,2] row_mask:0xf bank_mask:0xf bound_ctrl:1
	v_mov_b32_dpp v236, v249 quad_perm:[3,3,3,3] row_mask:0xf bank_mask:0xf bound_ctrl:1
	v_permlane16_swap_b32_e32 v108, v200
	v_permlane16_swap_b32_e32 v109, v201
	v_permlane16_swap_b32_e32 v110, v202
	v_permlane16_swap_b32_e32 v111, v203
	v_pk_fma_f32 v[8:9], v[108:109], v[230:231], v[8:9] op_sel_hi:[1,0,1]
	v_pk_fma_f32 v[10:11], v[110:111], v[230:231], v[10:11] op_sel_hi:[1,0,1]
	v_pk_fma_f32 v[12:13], v[200:201], v[230:231], v[12:13] op_sel_hi:[1,0,1]
	v_pk_fma_f32 v[14:15], v[202:203], v[230:231], v[14:15] op_sel_hi:[1,0,1]
	v_pk_fma_f32 v[16:17], v[108:109], v[232:233], v[16:17] op_sel_hi:[1,0,1]
	v_pk_fma_f32 v[18:19], v[110:111], v[232:233], v[18:19] op_sel_hi:[1,0,1]
	v_pk_fma_f32 v[20:21], v[200:201], v[232:233], v[20:21] op_sel_hi:[1,0,1]
	v_pk_fma_f32 v[22:23], v[202:203], v[232:233], v[22:23] op_sel_hi:[1,0,1]
	v_pk_fma_f32 v[24:25], v[108:109], v[234:235], v[24:25] op_sel_hi:[1,0,1]
	v_pk_fma_f32 v[26:27], v[110:111], v[234:235], v[26:27] op_sel_hi:[1,0,1]
	v_pk_fma_f32 v[28:29], v[200:201], v[234:235], v[28:29] op_sel_hi:[1,0,1]
	v_pk_fma_f32 v[30:31], v[202:203], v[234:235], v[30:31] op_sel_hi:[1,0,1]
	v_pk_fma_f32 v[32:33], v[108:109], v[236:237], v[32:33] op_sel_hi:[1,0,1]
	v_pk_fma_f32 v[34:35], v[110:111], v[236:237], v[34:35] op_sel_hi:[1,0,1]
	v_pk_fma_f32 v[36:37], v[200:201], v[236:237], v[36:37] op_sel_hi:[1,0,1]
	v_pk_fma_f32 v[38:39], v[202:203], v[236:237], v[38:39] op_sel_hi:[1,0,1]
	s_add_i32 s39, s39, 1
	s_lshr_b32 s33, s39, 4
	s_cmp_eq_u32 s33, 7
	s_cselect_b32 s36, s37, 0
	s_waitcnt vmcnt(17)
	v_mul_f32_e32 v212, v40, v112
	v_mul_f32_e32 v213, v44, v112
	v_mul_f32_e32 v214, v48, v112
	v_mul_f32_e32 v215, v52, v112
	v_mul_f32_e32 v216, v40, v120
	v_mul_f32_e32 v217, v44, v120
	v_mul_f32_e32 v218, v48, v120
	v_mul_f32_e32 v219, v52, v120
	v_fmac_f32_e32 v212, v113, v41
	v_fmac_f32_e32 v213, v113, v45
	v_fmac_f32_e32 v214, v113, v49
	v_fmac_f32_e32 v215, v113, v53
	v_fmac_f32_e32 v216, v121, v41
	v_fmac_f32_e32 v217, v121, v45
	v_fmac_f32_e32 v218, v121, v49
	v_fmac_f32_e32 v219, v121, v53
	v_fmac_f32_e32 v212, v114, v42
	v_fmac_f32_e32 v213, v114, v46
	v_fmac_f32_e32 v214, v114, v50
	v_fmac_f32_e32 v215, v114, v54
	v_fmac_f32_e32 v216, v122, v42
	v_fmac_f32_e32 v217, v122, v46
	v_fmac_f32_e32 v218, v122, v50
	v_fmac_f32_e32 v219, v122, v54
	v_fmac_f32_e32 v212, v115, v43
	v_fmac_f32_e32 v213, v115, v47
	v_fmac_f32_e32 v214, v115, v51
	v_fmac_f32_e32 v215, v115, v55
	v_fmac_f32_e32 v216, v123, v43
	v_fmac_f32_e32 v217, v123, v47
	v_fmac_f32_e32 v218, v123, v51
	v_fmac_f32_e32 v219, v123, v55
	v_cndmask_b32_e64 v241, v212, v213, s[8:9]
	v_cndmask_b32_e64 v245, v216, v217, s[8:9]
	v_cndmask_b32_e64 v243, v214, v215, s[8:9]
	v_cndmask_b32_e64 v247, v218, v219, s[8:9]
	v_cndmask_b32_e64 v240, v213, v212, s[8:9]
	v_cndmask_b32_e64 v244, v217, v216, s[8:9]
	v_cndmask_b32_e64 v242, v215, v214, s[8:9]
	v_cndmask_b32_e64 v246, v219, v218, s[8:9]
	v_add_f32_dpp v240, v241, v240 quad_perm:[1,0,3,2] row_mask:0xf bank_mask:0xf bound_ctrl:1
	v_add_f32_dpp v244, v245, v244 quad_perm:[1,0,3,2] row_mask:0xf bank_mask:0xf bound_ctrl:1
	v_add_f32_dpp v242, v243, v242 quad_perm:[1,0,3,2] row_mask:0xf bank_mask:0xf bound_ctrl:1
	v_add_f32_dpp v246, v247, v246 quad_perm:[1,0,3,2] row_mask:0xf bank_mask:0xf bound_ctrl:1
	v_cndmask_b32_e64 v213, v240, v242, s[34:35]
	v_cndmask_b32_e64 v217, v244, v246, s[34:35]
	v_cndmask_b32_e64 v212, v242, v240, s[34:35]
	v_cndmask_b32_e64 v216, v246, v244, s[34:35]
	s_nop 0
	v_add_f32_dpp v212, v213, v212 quad_perm:[2,3,0,1] row_mask:0xf bank_mask:0xf bound_ctrl:1
	v_add_f32_dpp v216, v217, v216 quad_perm:[2,3,0,1] row_mask:0xf bank_mask:0xf bound_ctrl:1
	s_nop 0
	v_add_f32_dpp v212, v212, v212 row_ror:4 row_mask:0xf bank_mask:0xf bound_ctrl:1
	v_add_f32_dpp v216, v216, v216 row_ror:4 row_mask:0xf bank_mask:0xf bound_ctrl:1
	s_nop 0
	v_add_f32_dpp v212, v212, v212 row_ror:8 row_mask:0xf bank_mask:0xf bound_ctrl:1
	v_add_f32_dpp v216, v216, v216 row_ror:8 row_mask:0xf bank_mask:0xf bound_ctrl:1
	s_cmp_lg_u32 s36, 0
	s_cbranch_scc1 .Ldq_bias_84

.Ldq_rescret_89:
	v_sub_f32_e32 v248, v216, v56
	v_exp_f32_e32 v249, v248
	s_waitcnt vmcnt(16)
	v_add_f32_e32 v57, v249, v57
	s_nop 0
	v_mov_b32_e32 v200, v124
	v_mov_b32_e32 v201, v125
	v_mov_b32_e32 v202, v126
	v_mov_b32_e32 v203, v127
	v_mov_b32_dpp v230, v249 quad_perm:[0,0,0,0] row_mask:0xf bank_mask:0xf bound_ctrl:1
	v_mov_b32_dpp v232, v249 quad_perm:[1,1,1,1] row_mask:0xf bank_mask:0xf bound_ctrl:1
	v_mov_b32_dpp v234, v249 quad_perm:[2,2,2,2] row_mask:0xf bank_mask:0xf bound_ctrl:1
	v_mov_b32_dpp v236, v249 quad_perm:[3,3,3,3] row_mask:0xf bank_mask:0xf bound_ctrl:1
	v_permlane16_swap_b32_e32 v124, v200
	v_permlane16_swap_b32_e32 v125, v201
	v_permlane16_swap_b32_e32 v126, v202
	v_permlane16_swap_b32_e32 v127, v203
	v_pk_fma_f32 v[8:9], v[124:125], v[230:231], v[8:9] op_sel_hi:[1,0,1]
	v_pk_fma_f32 v[10:11], v[126:127], v[230:231], v[10:11] op_sel_hi:[1,0,1]
	v_pk_fma_f32 v[12:13], v[200:201], v[230:231], v[12:13] op_sel_hi:[1,0,1]
	v_pk_fma_f32 v[14:15], v[202:203], v[230:231], v[14:15] op_sel_hi:[1,0,1]
	v_pk_fma_f32 v[16:17], v[124:125], v[232:233], v[16:17] op_sel_hi:[1,0,1]
	v_pk_fma_f32 v[18:19], v[126:127], v[232:233], v[18:19] op_sel_hi:[1,0,1]
	v_pk_fma_f32 v[20:21], v[200:201], v[232:233], v[20:21] op_sel_hi:[1,0,1]
	v_pk_fma_f32 v[22:23], v[202:203], v[232:233], v[22:23] op_sel_hi:[1,0,1]
	v_pk_fma_f32 v[24:25], v[124:125], v[234:235], v[24:25] op_sel_hi:[1,0,1]
	v_pk_fma_f32 v[26:27], v[126:127], v[234:235], v[26:27] op_sel_hi:[1,0,1]
	v_pk_fma_f32 v[28:29], v[200:201], v[234:235], v[28:29] op_sel_hi:[1,0,1]
	v_pk_fma_f32 v[30:31], v[202:203], v[234:235], v[30:31] op_sel_hi:[1,0,1]
	v_pk_fma_f32 v[32:33], v[124:125], v[236:237], v[32:33] op_sel_hi:[1,0,1]
	v_pk_fma_f32 v[34:35], v[126:127], v[236:237], v[34:35] op_sel_hi:[1,0,1]
	v_pk_fma_f32 v[36:37], v[200:201], v[236:237], v[36:37] op_sel_hi:[1,0,1]
	v_pk_fma_f32 v[38:39], v[202:203], v[236:237], v[38:39] op_sel_hi:[1,0,1]
	s_add_i32 s39, s39, 1
	s_lshr_b32 s33, s39, 4
	s_cmp_eq_u32 s33, 7
	s_cselect_b32 s36, s37, 0
	s_waitcnt vmcnt(13)
	v_mul_f32_e32 v212, v40, v128
	v_mul_f32_e32 v213, v44, v128
	v_mul_f32_e32 v214, v48, v128
	v_mul_f32_e32 v215, v52, v128
	v_mul_f32_e32 v216, v40, v136
	v_mul_f32_e32 v217, v44, v136
	v_mul_f32_e32 v218, v48, v136
	v_mul_f32_e32 v219, v52, v136
	v_fmac_f32_e32 v212, v129, v41
	v_fmac_f32_e32 v213, v129, v45
	v_fmac_f32_e32 v214, v129, v49
	v_fmac_f32_e32 v215, v129, v53
	v_fmac_f32_e32 v216, v137, v41
	v_fmac_f32_e32 v217, v137, v45
	v_fmac_f32_e32 v218, v137, v49
	v_fmac_f32_e32 v219, v137, v53
	v_fmac_f32_e32 v212, v130, v42
	v_fmac_f32_e32 v213, v130, v46
	v_fmac_f32_e32 v214, v130, v50
	v_fmac_f32_e32 v215, v130, v54
	v_fmac_f32_e32 v216, v138, v42
	v_fmac_f32_e32 v217, v138, v46
	v_fmac_f32_e32 v218, v138, v50
	v_fmac_f32_e32 v219, v138, v54
	v_fmac_f32_e32 v212, v131, v43
	v_fmac_f32_e32 v213, v131, v47
	v_fmac_f32_e32 v214, v131, v51
	v_fmac_f32_e32 v215, v131, v55
	v_fmac_f32_e32 v216, v139, v43
	v_fmac_f32_e32 v217, v139, v47
	v_fmac_f32_e32 v218, v139, v51
	v_fmac_f32_e32 v219, v139, v55
	v_cndmask_b32_e64 v241, v212, v213, s[8:9]
	v_cndmask_b32_e64 v245, v216, v217, s[8:9]
	v_cndmask_b32_e64 v243, v214, v215, s[8:9]
	v_cndmask_b32_e64 v247, v218, v219, s[8:9]
	v_cndmask_b32_e64 v240, v213, v212, s[8:9]
	v_cndmask_b32_e64 v244, v217, v216, s[8:9]
	v_cndmask_b32_e64 v242, v215, v214, s[8:9]
	v_cndmask_b32_e64 v246, v219, v218, s[8:9]
	v_add_f32_dpp v240, v241, v240 quad_perm:[1,0,3,2] row_mask:0xf bank_mask:0xf bound_ctrl:1
	v_add_f32_dpp v244, v245, v244 quad_perm:[1,0,3,2] row_mask:0xf bank_mask:0xf bound_ctrl:1
	v_add_f32_dpp v242, v243, v242 quad_perm:[1,0,3,2] row_mask:0xf bank_mask:0xf bound_ctrl:1
	v_add_f32_dpp v246, v247, v246 quad_perm:[1,0,3,2] row_mask:0xf bank_mask:0xf bound_ctrl:1
	v_cndmask_b32_e64 v213, v240, v242, s[34:35]
	v_cndmask_b32_e64 v217, v244, v246, s[34:35]
	v_cndmask_b32_e64 v212, v242, v240, s[34:35]
	v_cndmask_b32_e64 v216, v246, v244, s[34:35]
	s_nop 0
	v_add_f32_dpp v212, v213, v212 quad_perm:[2,3,0,1] row_mask:0xf bank_mask:0xf bound_ctrl:1
	v_add_f32_dpp v216, v217, v216 quad_perm:[2,3,0,1] row_mask:0xf bank_mask:0xf bound_ctrl:1
	s_nop 0
	v_add_f32_dpp v212, v212, v212 row_ror:4 row_mask:0xf bank_mask:0xf bound_ctrl:1
	v_add_f32_dpp v216, v216, v216 row_ror:4 row_mask:0xf bank_mask:0xf bound_ctrl:1
	s_nop 0
	v_add_f32_dpp v212, v212, v212 row_ror:8 row_mask:0xf bank_mask:0xf bound_ctrl:1
	v_add_f32_dpp v216, v216, v216 row_ror:8 row_mask:0xf bank_mask:0xf bound_ctrl:1
	s_cmp_lg_u32 s36, 0
	s_cbranch_scc1 .Ldq_bias_90

.Ldq_rescret_95:
	v_sub_f32_e32 v248, v216, v56
	v_exp_f32_e32 v249, v248
	s_waitcnt vmcnt(12)
	v_add_f32_e32 v57, v249, v57
	s_nop 0
	v_mov_b32_e32 v200, v140
	v_mov_b32_e32 v201, v141
	v_mov_b32_e32 v202, v142
	v_mov_b32_e32 v203, v143
	v_mov_b32_dpp v230, v249 quad_perm:[0,0,0,0] row_mask:0xf bank_mask:0xf bound_ctrl:1
	v_mov_b32_dpp v232, v249 quad_perm:[1,1,1,1] row_mask:0xf bank_mask:0xf bound_ctrl:1
	v_mov_b32_dpp v234, v249 quad_perm:[2,2,2,2] row_mask:0xf bank_mask:0xf bound_ctrl:1
	v_mov_b32_dpp v236, v249 quad_perm:[3,3,3,3] row_mask:0xf bank_mask:0xf bound_ctrl:1
	v_permlane16_swap_b32_e32 v140, v200
	v_permlane16_swap_b32_e32 v141, v201
	v_permlane16_swap_b32_e32 v142, v202
	v_permlane16_swap_b32_e32 v143, v203
	v_pk_fma_f32 v[8:9], v[140:141], v[230:231], v[8:9] op_sel_hi:[1,0,1]
	v_pk_fma_f32 v[10:11], v[142:143], v[230:231], v[10:11] op_sel_hi:[1,0,1]
	v_pk_fma_f32 v[12:13], v[200:201], v[230:231], v[12:13] op_sel_hi:[1,0,1]
	v_pk_fma_f32 v[14:15], v[202:203], v[230:231], v[14:15] op_sel_hi:[1,0,1]
	v_pk_fma_f32 v[16:17], v[140:141], v[232:233], v[16:17] op_sel_hi:[1,0,1]
	v_pk_fma_f32 v[18:19], v[142:143], v[232:233], v[18:19] op_sel_hi:[1,0,1]
	v_pk_fma_f32 v[20:21], v[200:201], v[232:233], v[20:21] op_sel_hi:[1,0,1]
	v_pk_fma_f32 v[22:23], v[202:203], v[232:233], v[22:23] op_sel_hi:[1,0,1]
	v_pk_fma_f32 v[24:25], v[140:141], v[234:235], v[24:25] op_sel_hi:[1,0,1]
	v_pk_fma_f32 v[26:27], v[142:143], v[234:235], v[26:27] op_sel_hi:[1,0,1]
	v_pk_fma_f32 v[28:29], v[200:201], v[234:235], v[28:29] op_sel_hi:[1,0,1]
	v_pk_fma_f32 v[30:31], v[202:203], v[234:235], v[30:31] op_sel_hi:[1,0,1]
	v_pk_fma_f32 v[32:33], v[140:141], v[236:237], v[32:33] op_sel_hi:[1,0,1]
	v_pk_fma_f32 v[34:35], v[142:143], v[236:237], v[34:35] op_sel_hi:[1,0,1]
	v_pk_fma_f32 v[36:37], v[200:201], v[236:237], v[36:37] op_sel_hi:[1,0,1]
	v_pk_fma_f32 v[38:39], v[202:203], v[236:237], v[38:39] op_sel_hi:[1,0,1]
	s_add_i32 s39, s39, 1
	s_lshr_b32 s33, s39, 4
	s_cmp_eq_u32 s33, 7
	s_cselect_b32 s36, s37, 0
	s_waitcnt vmcnt(9)
	v_mul_f32_e32 v212, v40, v144
	v_mul_f32_e32 v213, v44, v144
	v_mul_f32_e32 v214, v48, v144
	v_mul_f32_e32 v215, v52, v144
	v_mul_f32_e32 v216, v40, v152
	v_mul_f32_e32 v217, v44, v152
	v_mul_f32_e32 v218, v48, v152
	v_mul_f32_e32 v219, v52, v152
	v_fmac_f32_e32 v212, v145, v41
	v_fmac_f32_e32 v213, v145, v45
	v_fmac_f32_e32 v214, v145, v49
	v_fmac_f32_e32 v215, v145, v53
	v_fmac_f32_e32 v216, v153, v41
	v_fmac_f32_e32 v217, v153, v45
	v_fmac_f32_e32 v218, v153, v49
	v_fmac_f32_e32 v219, v153, v53
	v_fmac_f32_e32 v212, v146, v42
	v_fmac_f32_e32 v213, v146, v46
	v_fmac_f32_e32 v214, v146, v50
	v_fmac_f32_e32 v215, v146, v54
	v_fmac_f32_e32 v216, v154, v42
	v_fmac_f32_e32 v217, v154, v46
	v_fmac_f32_e32 v218, v154, v50
	v_fmac_f32_e32 v219, v154, v54
	v_fmac_f32_e32 v212, v147, v43
	v_fmac_f32_e32 v213, v147, v47
	v_fmac_f32_e32 v214, v147, v51
	v_fmac_f32_e32 v215, v147, v55
	v_fmac_f32_e32 v216, v155, v43
	v_fmac_f32_e32 v217, v155, v47
	v_fmac_f32_e32 v218, v155, v51
	v_fmac_f32_e32 v219, v155, v55
	v_cndmask_b32_e64 v241, v212, v213, s[8:9]
	v_cndmask_b32_e64 v245, v216, v217, s[8:9]
	v_cndmask_b32_e64 v243, v214, v215, s[8:9]
	v_cndmask_b32_e64 v247, v218, v219, s[8:9]
	v_cndmask_b32_e64 v240, v213, v212, s[8:9]
	v_cndmask_b32_e64 v244, v217, v216, s[8:9]
	v_cndmask_b32_e64 v242, v215, v214, s[8:9]
	v_cndmask_b32_e64 v246, v219, v218, s[8:9]
	v_add_f32_dpp v240, v241, v240 quad_perm:[1,0,3,2] row_mask:0xf bank_mask:0xf bound_ctrl:1
	v_add_f32_dpp v244, v245, v244 quad_perm:[1,0,3,2] row_mask:0xf bank_mask:0xf bound_ctrl:1
	v_add_f32_dpp v242, v243, v242 quad_perm:[1,0,3,2] row_mask:0xf bank_mask:0xf bound_ctrl:1
	v_add_f32_dpp v246, v247, v246 quad_perm:[1,0,3,2] row_mask:0xf bank_mask:0xf bound_ctrl:1
	v_cndmask_b32_e64 v213, v240, v242, s[34:35]
	v_cndmask_b32_e64 v217, v244, v246, s[34:35]
	v_cndmask_b32_e64 v212, v242, v240, s[34:35]
	v_cndmask_b32_e64 v216, v246, v244, s[34:35]
	s_nop 0
	v_add_f32_dpp v212, v213, v212 quad_perm:[2,3,0,1] row_mask:0xf bank_mask:0xf bound_ctrl:1
	v_add_f32_dpp v216, v217, v216 quad_perm:[2,3,0,1] row_mask:0xf bank_mask:0xf bound_ctrl:1
	s_nop 0
	v_add_f32_dpp v212, v212, v212 row_ror:4 row_mask:0xf bank_mask:0xf bound_ctrl:1
	v_add_f32_dpp v216, v216, v216 row_ror:4 row_mask:0xf bank_mask:0xf bound_ctrl:1
	s_nop 0
	v_add_f32_dpp v212, v212, v212 row_ror:8 row_mask:0xf bank_mask:0xf bound_ctrl:1
	v_add_f32_dpp v216, v216, v216 row_ror:8 row_mask:0xf bank_mask:0xf bound_ctrl:1
	s_cmp_lg_u32 s36, 0
	s_cbranch_scc1 .Ldq_bias_96

.Ldq_rescret_101:
	v_sub_f32_e32 v248, v216, v56
	v_exp_f32_e32 v249, v248
	s_waitcnt vmcnt(8)
	v_add_f32_e32 v57, v249, v57
	s_nop 0
	v_mov_b32_e32 v200, v156
	v_mov_b32_e32 v201, v157
	v_mov_b32_e32 v202, v158
	v_mov_b32_e32 v203, v159
	v_mov_b32_dpp v230, v249 quad_perm:[0,0,0,0] row_mask:0xf bank_mask:0xf bound_ctrl:1
	v_mov_b32_dpp v232, v249 quad_perm:[1,1,1,1] row_mask:0xf bank_mask:0xf bound_ctrl:1
	v_mov_b32_dpp v234, v249 quad_perm:[2,2,2,2] row_mask:0xf bank_mask:0xf bound_ctrl:1
	v_mov_b32_dpp v236, v249 quad_perm:[3,3,3,3] row_mask:0xf bank_mask:0xf bound_ctrl:1
	v_permlane16_swap_b32_e32 v156, v200
	v_permlane16_swap_b32_e32 v157, v201
	v_permlane16_swap_b32_e32 v158, v202
	v_permlane16_swap_b32_e32 v159, v203
	v_pk_fma_f32 v[8:9], v[156:157], v[230:231], v[8:9] op_sel_hi:[1,0,1]
	v_pk_fma_f32 v[10:11], v[158:159], v[230:231], v[10:11] op_sel_hi:[1,0,1]
	v_pk_fma_f32 v[12:13], v[200:201], v[230:231], v[12:13] op_sel_hi:[1,0,1]
	v_pk_fma_f32 v[14:15], v[202:203], v[230:231], v[14:15] op_sel_hi:[1,0,1]
	v_pk_fma_f32 v[16:17], v[156:157], v[232:233], v[16:17] op_sel_hi:[1,0,1]
	v_pk_fma_f32 v[18:19], v[158:159], v[232:233], v[18:19] op_sel_hi:[1,0,1]
	v_pk_fma_f32 v[20:21], v[200:201], v[232:233], v[20:21] op_sel_hi:[1,0,1]
	v_pk_fma_f32 v[22:23], v[202:203], v[232:233], v[22:23] op_sel_hi:[1,0,1]
	v_pk_fma_f32 v[24:25], v[156:157], v[234:235], v[24:25] op_sel_hi:[1,0,1]
	v_pk_fma_f32 v[26:27], v[158:159], v[234:235], v[26:27] op_sel_hi:[1,0,1]
	v_pk_fma_f32 v[28:29], v[200:201], v[234:235], v[28:29] op_sel_hi:[1,0,1]
	v_pk_fma_f32 v[30:31], v[202:203], v[234:235], v[30:31] op_sel_hi:[1,0,1]
	v_pk_fma_f32 v[32:33], v[156:157], v[236:237], v[32:33] op_sel_hi:[1,0,1]
	v_pk_fma_f32 v[34:35], v[158:159], v[236:237], v[34:35] op_sel_hi:[1,0,1]
	v_pk_fma_f32 v[36:37], v[200:201], v[236:237], v[36:37] op_sel_hi:[1,0,1]
	v_pk_fma_f32 v[38:39], v[202:203], v[236:237], v[38:39] op_sel_hi:[1,0,1]
	s_add_i32 s39, s39, 1
	s_lshr_b32 s33, s39, 4
	s_cmp_eq_u32 s33, 7
	s_cselect_b32 s36, s37, 0
	s_waitcnt vmcnt(5)
	v_mul_f32_e32 v212, v40, v64
	v_mul_f32_e32 v213, v44, v64
	v_mul_f32_e32 v214, v48, v64
	v_mul_f32_e32 v215, v52, v64
	v_mul_f32_e32 v216, v40, v72
	v_mul_f32_e32 v217, v44, v72
	v_mul_f32_e32 v218, v48, v72
	v_mul_f32_e32 v219, v52, v72
	v_fmac_f32_e32 v212, v65, v41
	v_fmac_f32_e32 v213, v65, v45
	v_fmac_f32_e32 v214, v65, v49
	v_fmac_f32_e32 v215, v65, v53
	v_fmac_f32_e32 v216, v73, v41
	v_fmac_f32_e32 v217, v73, v45
	v_fmac_f32_e32 v218, v73, v49
	v_fmac_f32_e32 v219, v73, v53
	v_fmac_f32_e32 v212, v66, v42
	v_fmac_f32_e32 v213, v66, v46
	v_fmac_f32_e32 v214, v66, v50
	v_fmac_f32_e32 v215, v66, v54
	v_fmac_f32_e32 v216, v74, v42
	v_fmac_f32_e32 v217, v74, v46
	v_fmac_f32_e32 v218, v74, v50
	v_fmac_f32_e32 v219, v74, v54
	v_fmac_f32_e32 v212, v67, v43
	v_fmac_f32_e32 v213, v67, v47
	v_fmac_f32_e32 v214, v67, v51
	v_fmac_f32_e32 v215, v67, v55
	v_fmac_f32_e32 v216, v75, v43
	v_fmac_f32_e32 v217, v75, v47
	v_fmac_f32_e32 v218, v75, v51
	v_fmac_f32_e32 v219, v75, v55
	v_cndmask_b32_e64 v241, v212, v213, s[8:9]
	v_cndmask_b32_e64 v245, v216, v217, s[8:9]
	v_cndmask_b32_e64 v243, v214, v215, s[8:9]
	v_cndmask_b32_e64 v247, v218, v219, s[8:9]
	v_cndmask_b32_e64 v240, v213, v212, s[8:9]
	v_cndmask_b32_e64 v244, v217, v216, s[8:9]
	v_cndmask_b32_e64 v242, v215, v214, s[8:9]
	v_cndmask_b32_e64 v246, v219, v218, s[8:9]
	v_add_f32_dpp v240, v241, v240 quad_perm:[1,0,3,2] row_mask:0xf bank_mask:0xf bound_ctrl:1
	v_add_f32_dpp v244, v245, v244 quad_perm:[1,0,3,2] row_mask:0xf bank_mask:0xf bound_ctrl:1
	v_add_f32_dpp v242, v243, v242 quad_perm:[1,0,3,2] row_mask:0xf bank_mask:0xf bound_ctrl:1
	v_add_f32_dpp v246, v247, v246 quad_perm:[1,0,3,2] row_mask:0xf bank_mask:0xf bound_ctrl:1
	v_cndmask_b32_e64 v213, v240, v242, s[34:35]
	v_cndmask_b32_e64 v217, v244, v246, s[34:35]
	v_cndmask_b32_e64 v212, v242, v240, s[34:35]
	v_cndmask_b32_e64 v216, v246, v244, s[34:35]
	s_nop 0
	v_add_f32_dpp v212, v213, v212 quad_perm:[2,3,0,1] row_mask:0xf bank_mask:0xf bound_ctrl:1
	v_add_f32_dpp v216, v217, v216 quad_perm:[2,3,0,1] row_mask:0xf bank_mask:0xf bound_ctrl:1
	s_nop 0
	v_add_f32_dpp v212, v212, v212 row_ror:4 row_mask:0xf bank_mask:0xf bound_ctrl:1
	v_add_f32_dpp v216, v216, v216 row_ror:4 row_mask:0xf bank_mask:0xf bound_ctrl:1
	s_nop 0
	v_add_f32_dpp v212, v212, v212 row_ror:8 row_mask:0xf bank_mask:0xf bound_ctrl:1
	v_add_f32_dpp v216, v216, v216 row_ror:8 row_mask:0xf bank_mask:0xf bound_ctrl:1
	s_cmp_lg_u32 s36, 0
	s_cbranch_scc1 .Ldq_bias_102

.Ldq_rescret_107:
	v_sub_f32_e32 v248, v216, v56
	v_exp_f32_e32 v249, v248
	s_waitcnt vmcnt(4)
	v_add_f32_e32 v57, v249, v57
	s_nop 0
	v_mov_b32_e32 v200, v76
	v_mov_b32_e32 v201, v77
	v_mov_b32_e32 v202, v78
	v_mov_b32_e32 v203, v79
	v_mov_b32_dpp v230, v249 quad_perm:[0,0,0,0] row_mask:0xf bank_mask:0xf bound_ctrl:1
	v_mov_b32_dpp v232, v249 quad_perm:[1,1,1,1] row_mask:0xf bank_mask:0xf bound_ctrl:1
	v_mov_b32_dpp v234, v249 quad_perm:[2,2,2,2] row_mask:0xf bank_mask:0xf bound_ctrl:1
	v_mov_b32_dpp v236, v249 quad_perm:[3,3,3,3] row_mask:0xf bank_mask:0xf bound_ctrl:1
	v_permlane16_swap_b32_e32 v76, v200
	v_permlane16_swap_b32_e32 v77, v201
	v_permlane16_swap_b32_e32 v78, v202
	v_permlane16_swap_b32_e32 v79, v203
	v_pk_fma_f32 v[8:9], v[76:77], v[230:231], v[8:9] op_sel_hi:[1,0,1]
	v_pk_fma_f32 v[10:11], v[78:79], v[230:231], v[10:11] op_sel_hi:[1,0,1]
	v_pk_fma_f32 v[12:13], v[200:201], v[230:231], v[12:13] op_sel_hi:[1,0,1]
	v_pk_fma_f32 v[14:15], v[202:203], v[230:231], v[14:15] op_sel_hi:[1,0,1]
	v_pk_fma_f32 v[16:17], v[76:77], v[232:233], v[16:17] op_sel_hi:[1,0,1]
	v_pk_fma_f32 v[18:19], v[78:79], v[232:233], v[18:19] op_sel_hi:[1,0,1]
	v_pk_fma_f32 v[20:21], v[200:201], v[232:233], v[20:21] op_sel_hi:[1,0,1]
	v_pk_fma_f32 v[22:23], v[202:203], v[232:233], v[22:23] op_sel_hi:[1,0,1]
	v_pk_fma_f32 v[24:25], v[76:77], v[234:235], v[24:25] op_sel_hi:[1,0,1]
	v_pk_fma_f32 v[26:27], v[78:79], v[234:235], v[26:27] op_sel_hi:[1,0,1]
	v_pk_fma_f32 v[28:29], v[200:201], v[234:235], v[28:29] op_sel_hi:[1,0,1]
	v_pk_fma_f32 v[30:31], v[202:203], v[234:235], v[30:31] op_sel_hi:[1,0,1]
	v_pk_fma_f32 v[32:33], v[76:77], v[236:237], v[32:33] op_sel_hi:[1,0,1]
	v_pk_fma_f32 v[34:35], v[78:79], v[236:237], v[34:35] op_sel_hi:[1,0,1]
	v_pk_fma_f32 v[36:37], v[200:201], v[236:237], v[36:37] op_sel_hi:[1,0,1]
	v_pk_fma_f32 v[38:39], v[202:203], v[236:237], v[38:39] op_sel_hi:[1,0,1]
	s_add_i32 s39, s39, 1
	s_lshr_b32 s33, s39, 4
	s_cmp_eq_u32 s33, 7
	s_cselect_b32 s36, s37, 0
	s_waitcnt vmcnt(1)
	v_mul_f32_e32 v212, v40, v80
	v_mul_f32_e32 v213, v44, v80
	v_mul_f32_e32 v214, v48, v80
	v_mul_f32_e32 v215, v52, v80
	v_mul_f32_e32 v216, v40, v88
	v_mul_f32_e32 v217, v44, v88
	v_mul_f32_e32 v218, v48, v88
	v_mul_f32_e32 v219, v52, v88
	v_fmac_f32_e32 v212, v81, v41
	v_fmac_f32_e32 v213, v81, v45
	v_fmac_f32_e32 v214, v81, v49
	v_fmac_f32_e32 v215, v81, v53
	v_fmac_f32_e32 v216, v89, v41
	v_fmac_f32_e32 v217, v89, v45
	v_fmac_f32_e32 v218, v89, v49
	v_fmac_f32_e32 v219, v89, v53
	v_fmac_f32_e32 v212, v82, v42
	v_fmac_f32_e32 v213, v82, v46
	v_fmac_f32_e32 v214, v82, v50
	v_fmac_f32_e32 v215, v82, v54
	v_fmac_f32_e32 v216, v90, v42
	v_fmac_f32_e32 v217, v90, v46
	v_fmac_f32_e32 v218, v90, v50
	v_fmac_f32_e32 v219, v90, v54
	v_fmac_f32_e32 v212, v83, v43
	v_fmac_f32_e32 v213, v83, v47
	v_fmac_f32_e32 v214, v83, v51
	v_fmac_f32_e32 v215, v83, v55
	v_fmac_f32_e32 v216, v91, v43
	v_fmac_f32_e32 v217, v91, v47
	v_fmac_f32_e32 v218, v91, v51
	v_fmac_f32_e32 v219, v91, v55
	v_cndmask_b32_e64 v241, v212, v213, s[8:9]
	v_cndmask_b32_e64 v245, v216, v217, s[8:9]
	v_cndmask_b32_e64 v243, v214, v215, s[8:9]
	v_cndmask_b32_e64 v247, v218, v219, s[8:9]
	v_cndmask_b32_e64 v240, v213, v212, s[8:9]
	v_cndmask_b32_e64 v244, v217, v216, s[8:9]
	v_cndmask_b32_e64 v242, v215, v214, s[8:9]
	v_cndmask_b32_e64 v246, v219, v218, s[8:9]
	v_add_f32_dpp v240, v241, v240 quad_perm:[1,0,3,2] row_mask:0xf bank_mask:0xf bound_ctrl:1
	v_add_f32_dpp v244, v245, v244 quad_perm:[1,0,3,2] row_mask:0xf bank_mask:0xf bound_ctrl:1
	v_add_f32_dpp v242, v243, v242 quad_perm:[1,0,3,2] row_mask:0xf bank_mask:0xf bound_ctrl:1
	v_add_f32_dpp v246, v247, v246 quad_perm:[1,0,3,2] row_mask:0xf bank_mask:0xf bound_ctrl:1
	v_cndmask_b32_e64 v213, v240, v242, s[34:35]
	v_cndmask_b32_e64 v217, v244, v246, s[34:35]
	v_cndmask_b32_e64 v212, v242, v240, s[34:35]
	v_cndmask_b32_e64 v216, v246, v244, s[34:35]
	s_nop 0
	v_add_f32_dpp v212, v213, v212 quad_perm:[2,3,0,1] row_mask:0xf bank_mask:0xf bound_ctrl:1
	v_add_f32_dpp v216, v217, v216 quad_perm:[2,3,0,1] row_mask:0xf bank_mask:0xf bound_ctrl:1
	s_nop 0
	v_add_f32_dpp v212, v212, v212 row_ror:4 row_mask:0xf bank_mask:0xf bound_ctrl:1
	v_add_f32_dpp v216, v216, v216 row_ror:4 row_mask:0xf bank_mask:0xf bound_ctrl:1
	s_nop 0
	v_add_f32_dpp v212, v212, v212 row_ror:8 row_mask:0xf bank_mask:0xf bound_ctrl:1
	v_add_f32_dpp v216, v216, v216 row_ror:8 row_mask:0xf bank_mask:0xf bound_ctrl:1
	s_cmp_lg_u32 s36, 0
	s_cbranch_scc1 .Ldq_bias_108

.Ldq_rescret_113:
	v_sub_f32_e32 v248, v216, v56
	v_exp_f32_e32 v249, v248
	s_waitcnt vmcnt(0)
	v_add_f32_e32 v57, v249, v57
	s_nop 0
	v_mov_b32_e32 v200, v92
	v_mov_b32_e32 v201, v93
	v_mov_b32_e32 v202, v94
	v_mov_b32_e32 v203, v95
	v_mov_b32_dpp v230, v249 quad_perm:[0,0,0,0] row_mask:0xf bank_mask:0xf bound_ctrl:1
	v_mov_b32_dpp v232, v249 quad_perm:[1,1,1,1] row_mask:0xf bank_mask:0xf bound_ctrl:1
	v_mov_b32_dpp v234, v249 quad_perm:[2,2,2,2] row_mask:0xf bank_mask:0xf bound_ctrl:1
	v_mov_b32_dpp v236, v249 quad_perm:[3,3,3,3] row_mask:0xf bank_mask:0xf bound_ctrl:1
	v_permlane16_swap_b32_e32 v92, v200
	v_permlane16_swap_b32_e32 v93, v201
	v_permlane16_swap_b32_e32 v94, v202
	v_permlane16_swap_b32_e32 v95, v203
	v_pk_fma_f32 v[8:9], v[92:93], v[230:231], v[8:9] op_sel_hi:[1,0,1]
	v_pk_fma_f32 v[10:11], v[94:95], v[230:231], v[10:11] op_sel_hi:[1,0,1]
	v_pk_fma_f32 v[12:13], v[200:201], v[230:231], v[12:13] op_sel_hi:[1,0,1]
	v_pk_fma_f32 v[14:15], v[202:203], v[230:231], v[14:15] op_sel_hi:[1,0,1]
	v_pk_fma_f32 v[16:17], v[92:93], v[232:233], v[16:17] op_sel_hi:[1,0,1]
	v_pk_fma_f32 v[18:19], v[94:95], v[232:233], v[18:19] op_sel_hi:[1,0,1]
	v_pk_fma_f32 v[20:21], v[200:201], v[232:233], v[20:21] op_sel_hi:[1,0,1]
	v_pk_fma_f32 v[22:23], v[202:203], v[232:233], v[22:23] op_sel_hi:[1,0,1]
	v_pk_fma_f32 v[24:25], v[92:93], v[234:235], v[24:25] op_sel_hi:[1,0,1]
	v_pk_fma_f32 v[26:27], v[94:95], v[234:235], v[26:27] op_sel_hi:[1,0,1]
	v_pk_fma_f32 v[28:29], v[200:201], v[234:235], v[28:29] op_sel_hi:[1,0,1]
	v_pk_fma_f32 v[30:31], v[202:203], v[234:235], v[30:31] op_sel_hi:[1,0,1]
	v_pk_fma_f32 v[32:33], v[92:93], v[236:237], v[32:33] op_sel_hi:[1,0,1]
	v_pk_fma_f32 v[34:35], v[94:95], v[236:237], v[34:35] op_sel_hi:[1,0,1]
	v_pk_fma_f32 v[36:37], v[200:201], v[236:237], v[36:37] op_sel_hi:[1,0,1]
	v_pk_fma_f32 v[38:39], v[202:203], v[236:237], v[38:39] op_sel_hi:[1,0,1]
	v_mov_b32_e32 v64, v56
	v_mov_b32_e32 v65, v57
	v_mov_b32_e32 v66, v8
	v_mov_b32_e32 v67, v9
	v_mov_b32_e32 v68, v10
	v_mov_b32_e32 v69, v11
	v_mov_b32_e32 v70, v12
	v_mov_b32_e32 v71, v13
	v_mov_b32_e32 v72, v14
	v_mov_b32_e32 v73, v15
	v_mov_b32_e32 v74, v16
	v_mov_b32_e32 v75, v17
	v_mov_b32_e32 v76, v18
	v_mov_b32_e32 v77, v19
	v_mov_b32_e32 v78, v20
	v_mov_b32_e32 v79, v21
	v_mov_b32_e32 v80, v22
	v_mov_b32_e32 v81, v23
	v_mov_b32_e32 v82, v24
	v_mov_b32_e32 v83, v25
	v_mov_b32_e32 v84, v26
	v_mov_b32_e32 v85, v27
	v_mov_b32_e32 v86, v28
	v_mov_b32_e32 v87, v29
	v_mov_b32_e32 v88, v30
	v_mov_b32_e32 v89, v31
	v_mov_b32_e32 v90, v32
	v_mov_b32_e32 v91, v33
	v_mov_b32_e32 v92, v34
	v_mov_b32_e32 v93, v35
	v_mov_b32_e32 v94, v36
	v_mov_b32_e32 v95, v37
	v_mov_b32_e32 v96, v38
	v_mov_b32_e32 v97, v39
	s_nop 1
	v_permlane32_swap_b32_e32 v56, v64
	v_permlane32_swap_b32_e32 v57, v65
	v_permlane32_swap_b32_e32 v8, v66
	v_permlane32_swap_b32_e32 v9, v67
	v_permlane32_swap_b32_e32 v10, v68
	v_permlane32_swap_b32_e32 v11, v69
	v_permlane32_swap_b32_e32 v12, v70
	v_permlane32_swap_b32_e32 v13, v71
	v_permlane32_swap_b32_e32 v14, v72
	v_permlane32_swap_b32_e32 v15, v73
	v_permlane32_swap_b32_e32 v16, v74
	v_permlane32_swap_b32_e32 v17, v75
	v_permlane32_swap_b32_e32 v18, v76
	v_permlane32_swap_b32_e32 v19, v77
	v_permlane32_swap_b32_e32 v20, v78
	v_permlane32_swap_b32_e32 v21, v79
	v_permlane32_swap_b32_e32 v22, v80
	v_permlane32_swap_b32_e32 v23, v81
	v_permlane32_swap_b32_e32 v24, v82
	v_permlane32_swap_b32_e32 v25, v83
	v_permlane32_swap_b32_e32 v26, v84
	v_permlane32_swap_b32_e32 v27, v85
	v_permlane32_swap_b32_e32 v28, v86
	v_permlane32_swap_b32_e32 v29, v87
	v_permlane32_swap_b32_e32 v30, v88
	v_permlane32_swap_b32_e32 v31, v89
	v_permlane32_swap_b32_e32 v32, v90
	v_permlane32_swap_b32_e32 v33, v91
	v_permlane32_swap_b32_e32 v34, v92
	v_permlane32_swap_b32_e32 v35, v93
	v_permlane32_swap_b32_e32 v36, v94
	v_permlane32_swap_b32_e32 v37, v95
	v_permlane32_swap_b32_e32 v38, v96
	v_permlane32_swap_b32_e32 v39, v97
	v_max_f32_e32 v248, v56, v56
	v_max_f32_e32 v249, v64, v64
	v_max_f32_e32 v248, v248, v249
	v_sub_f32_e32 v249, v56, v248
	v_sub_f32_e32 v250, v64, v248
	v_exp_f32_e32 v249, v249
	v_exp_f32_e32 v250, v250
	v_mov_b32_e32 v56, v248
	s_nop 0
	v_mul_f32_e32 v65, v250, v65
	v_fmac_f32_e32 v65, v57, v249
	v_mov_b32_dpp v220, v249 quad_perm:[0,0,0,0] row_mask:0xf bank_mask:0xf bound_ctrl:1
	v_mov_b32_dpp v230, v250 quad_perm:[0,0,0,0] row_mask:0xf bank_mask:0xf bound_ctrl:1
	v_mov_b32_dpp v222, v249 quad_perm:[1,1,1,1] row_mask:0xf bank_mask:0xf bound_ctrl:1
	v_mov_b32_dpp v232, v250 quad_perm:[1,1,1,1] row_mask:0xf bank_mask:0xf bound_ctrl:1
	v_mov_b32_dpp v224, v249 quad_perm:[2,2,2,2] row_mask:0xf bank_mask:0xf bound_ctrl:1
	v_mov_b32_dpp v234, v250 quad_perm:[2,2,2,2] row_mask:0xf bank_mask:0xf bound_ctrl:1
	v_mov_b32_dpp v226, v249 quad_perm:[3,3,3,3] row_mask:0xf bank_mask:0xf bound_ctrl:1
	v_mov_b32_dpp v236, v250 quad_perm:[3,3,3,3] row_mask:0xf bank_mask:0xf bound_ctrl:1
	v_pk_mul_f32 v[66:67], v[230:231], v[66:67] op_sel_hi:[0,1]
	v_pk_fma_f32 v[8:9], v[8:9], v[220:221], v[66:67] op_sel_hi:[1,0,1]
	v_pk_mul_f32 v[68:69], v[230:231], v[68:69] op_sel_hi:[0,1]
	v_pk_fma_f32 v[10:11], v[10:11], v[220:221], v[68:69] op_sel_hi:[1,0,1]
	v_pk_mul_f32 v[70:71], v[230:231], v[70:71] op_sel_hi:[0,1]
	v_pk_fma_f32 v[12:13], v[12:13], v[220:221], v[70:71] op_sel_hi:[1,0,1]
	v_pk_mul_f32 v[72:73], v[230:231], v[72:73] op_sel_hi:[0,1]
	v_pk_fma_f32 v[14:15], v[14:15], v[220:221], v[72:73] op_sel_hi:[1,0,1]
	v_pk_mul_f32 v[74:75], v[232:233], v[74:75] op_sel_hi:[0,1]
	v_pk_fma_f32 v[16:17], v[16:17], v[222:223], v[74:75] op_sel_hi:[1,0,1]
	v_pk_mul_f32 v[76:77], v[232:233], v[76:77] op_sel_hi:[0,1]
	v_pk_fma_f32 v[18:19], v[18:19], v[222:223], v[76:77] op_sel_hi:[1,0,1]
	v_pk_mul_f32 v[78:79], v[232:233], v[78:79] op_sel_hi:[0,1]
	v_pk_fma_f32 v[20:21], v[20:21], v[222:223], v[78:79] op_sel_hi:[1,0,1]
	v_pk_mul_f32 v[80:81], v[232:233], v[80:81] op_sel_hi:[0,1]
	v_pk_fma_f32 v[22:23], v[22:23], v[222:223], v[80:81] op_sel_hi:[1,0,1]
	v_pk_mul_f32 v[82:83], v[234:235], v[82:83] op_sel_hi:[0,1]
	v_pk_fma_f32 v[24:25], v[24:25], v[224:225], v[82:83] op_sel_hi:[1,0,1]
	v_pk_mul_f32 v[84:85], v[234:235], v[84:85] op_sel_hi:[0,1]
	v_pk_fma_f32 v[26:27], v[26:27], v[224:225], v[84:85] op_sel_hi:[1,0,1]
	v_pk_mul_f32 v[86:87], v[234:235], v[86:87] op_sel_hi:[0,1]
	v_pk_fma_f32 v[28:29], v[28:29], v[224:225], v[86:87] op_sel_hi:[1,0,1]
	v_pk_mul_f32 v[88:89], v[234:235], v[88:89] op_sel_hi:[0,1]
	v_pk_fma_f32 v[30:31], v[30:31], v[224:225], v[88:89] op_sel_hi:[1,0,1]
	v_pk_mul_f32 v[90:91], v[236:237], v[90:91] op_sel_hi:[0,1]
	v_pk_fma_f32 v[32:33], v[32:33], v[226:227], v[90:91] op_sel_hi:[1,0,1]
	v_pk_mul_f32 v[92:93], v[236:237], v[92:93] op_sel_hi:[0,1]
	v_pk_fma_f32 v[34:35], v[34:35], v[226:227], v[92:93] op_sel_hi:[1,0,1]
	v_pk_mul_f32 v[94:95], v[236:237], v[94:95] op_sel_hi:[0,1]
	v_pk_fma_f32 v[36:37], v[36:37], v[226:227], v[94:95] op_sel_hi:[1,0,1]
	v_pk_mul_f32 v[96:97], v[236:237], v[96:97] op_sel_hi:[0,1]
	v_pk_fma_f32 v[38:39], v[38:39], v[226:227], v[96:97] op_sel_hi:[1,0,1]
	v_bfe_u32 v240, v228, 4, 1
	s_and_b32 s33, s22, -16
	s_or_b32 s33, s33, s63
	s_bfe_u32 s57, s22, 0x20002
	s_or_b32 s33, s33, s57
	s_lshl_b32 s33, s33, 3
	v_lshl_add_u32 v248, v240, 2, s33
	v_lshlrev_b32_e32 v249, 9, v248
	v_lshl_add_u32 v249, v3, 4, v249
	v_add_u32_e32 v248, v248, v3
	v_lshlrev_b32_e32 v248, 3, v248
	v_mov_b32_e32 v57, v65
	v_cmp_gt_u32_e32 vcc, 32, v228
	s_and_saveexec_b64 s[0:1], vcc
	s_cbranch_execz .LBB0_755
	global_store_dwordx4 v249, v[8:11], s[10:11] offset:0
	global_store_dwordx4 v249, v[12:15], s[10:11] offset:256
	global_store_dwordx4 v249, v[16:19], s[10:11] offset:512
	global_store_dwordx4 v249, v[20:23], s[10:11] offset:768
	global_store_dwordx4 v249, v[24:27], s[10:11] offset:1024
	global_store_dwordx4 v249, v[28:31], s[10:11] offset:1280
	global_store_dwordx4 v249, v[32:35], s[10:11] offset:1536
	global_store_dwordx4 v249, v[36:39], s[10:11] offset:1792
	v_cmp_gt_u32_e32 vcc, 4, v3
	s_and_b64 exec, exec, vcc
	s_cbranch_execz .LBB0_755
	global_store_dwordx2 v248, v[56:57], s[12:13]
	s_branch .LBB0_755
.Ldq_np_1:
	s_lshr_b32 s33, s23, 4
	s_cmp_eq_u32 s33, 1
	s_cselect_b32 s57, s25, s24
	s_cmp_eq_u32 s33, 2
	s_cselect_b32 s57, s26, s57
	s_cmp_eq_u32 s33, 3
	s_cselect_b32 s57, s27, s57
	s_cmp_eq_u32 s33, 4
	s_cselect_b32 s57, s28, s57
	s_cmp_eq_u32 s33, 5
	s_cselect_b32 s57, s29, s57
	s_cmp_eq_u32 s33, 6
	s_cselect_b32 s57, s30, s57
	s_cmp_eq_u32 s33, 7
	s_cselect_b32 s57, s31, s57
	s_lshl_b32 s57, s57, 18
	s_add_u32 s4, s44, s57
	s_addc_u32 s5, s45, 0
	s_add_u32 s4, s4, 0x1000
	s_addc_u32 s5, s5, 0
	s_add_u32 s6, s46, s57
	s_addc_u32 s7, s47, 0
	s_add_u32 s6, s6, 0x1000
	s_addc_u32 s7, s7, 0
	s_branch .Ldq_npret_2

.Ldq_bias_14:
	s_and_b32 s33, s39, 15
	s_lshl_b32 s33, s33, 2
	s_add_i32 s33, s33, s60
	v_subrev_u32_e32 v248, s33, v62
	v_add_u32_e32 v249, -2, v248
	v_min_i32_e32 v248, -1, v248
	v_min_i32_e32 v249, -1, v249
	v_lshl_add_u32 v248, v248, 2, s93
	v_lshl_add_u32 v249, v249, 2, s93
	ds_read_b32 v248, v248 offset:512
	ds_read_b32 v249, v249 offset:512
	s_waitcnt lgkmcnt(0)
	v_add_f32_e32 v212, v212, v248
	v_add_f32_e32 v216, v216, v249
	s_branch .Ldq_biasret_15
.Ldq_resc_16:
	v_max_f32_e32 v248, v212, v212
	v_max_f32_e32 v249, v56, v56
	v_max_f32_e32 v249, v249, v248
	v_sub_f32_e32 v248, v56, v249
	v_exp_f32_e32 v250, v248
	v_mov_b32_e32 v56, v249
	s_nop 0
	v_mul_f32_e32 v57, v57, v250
	v_mov_b32_dpp v220, v250 quad_perm:[0,0,0,0] row_mask:0xf bank_mask:0xf bound_ctrl:1
	v_mov_b32_dpp v222, v250 quad_perm:[1,1,1,1] row_mask:0xf bank_mask:0xf bound_ctrl:1
	v_mov_b32_dpp v224, v250 quad_perm:[2,2,2,2] row_mask:0xf bank_mask:0xf bound_ctrl:1
	v_mov_b32_dpp v226, v250 quad_perm:[3,3,3,3] row_mask:0xf bank_mask:0xf bound_ctrl:1
	v_pk_mul_f32 v[8:9], v[8:9], v[220:221] op_sel_hi:[1,0]
	v_pk_mul_f32 v[10:11], v[10:11], v[220:221] op_sel_hi:[1,0]
	v_pk_mul_f32 v[12:13], v[12:13], v[220:221] op_sel_hi:[1,0]
	v_pk_mul_f32 v[14:15], v[14:15], v[220:221] op_sel_hi:[1,0]
	v_pk_mul_f32 v[16:17], v[16:17], v[222:223] op_sel_hi:[1,0]
	v_pk_mul_f32 v[18:19], v[18:19], v[222:223] op_sel_hi:[1,0]
	v_pk_mul_f32 v[20:21], v[20:21], v[222:223] op_sel_hi:[1,0]
	v_pk_mul_f32 v[22:23], v[22:23], v[222:223] op_sel_hi:[1,0]
	v_pk_mul_f32 v[24:25], v[24:25], v[224:225] op_sel_hi:[1,0]
	v_pk_mul_f32 v[26:27], v[26:27], v[224:225] op_sel_hi:[1,0]
	v_pk_mul_f32 v[28:29], v[28:29], v[224:225] op_sel_hi:[1,0]
	v_pk_mul_f32 v[30:31], v[30:31], v[224:225] op_sel_hi:[1,0]
	v_pk_mul_f32 v[32:33], v[32:33], v[226:227] op_sel_hi:[1,0]
	v_pk_mul_f32 v[34:35], v[34:35], v[226:227] op_sel_hi:[1,0]
	v_pk_mul_f32 v[36:37], v[36:37], v[226:227] op_sel_hi:[1,0]
	v_pk_mul_f32 v[38:39], v[38:39], v[226:227] op_sel_hi:[1,0]
	s_branch .Ldq_rescret_17
.Ldq_resc_18:
	v_max_f32_e32 v248, v216, v216
	v_max_f32_e32 v249, v56, v56
	v_max_f32_e32 v249, v249, v248
	v_sub_f32_e32 v248, v56, v249
	v_exp_f32_e32 v250, v248
	v_mov_b32_e32 v56, v249
	s_nop 0
	v_mul_f32_e32 v57, v57, v250
	v_mov_b32_dpp v220, v250 quad_perm:[0,0,0,0] row_mask:0xf bank_mask:0xf bound_ctrl:1
	v_mov_b32_dpp v222, v250 quad_perm:[1,1,1,1] row_mask:0xf bank_mask:0xf bound_ctrl:1
	v_mov_b32_dpp v224, v250 quad_perm:[2,2,2,2] row_mask:0xf bank_mask:0xf bound_ctrl:1
	v_mov_b32_dpp v226, v250 quad_perm:[3,3,3,3] row_mask:0xf bank_mask:0xf bound_ctrl:1
	v_pk_mul_f32 v[8:9], v[8:9], v[220:221] op_sel_hi:[1,0]
	v_pk_mul_f32 v[10:11], v[10:11], v[220:221] op_sel_hi:[1,0]
	v_pk_mul_f32 v[12:13], v[12:13], v[220:221] op_sel_hi:[1,0]
	v_pk_mul_f32 v[14:15], v[14:15], v[220:221] op_sel_hi:[1,0]
	v_pk_mul_f32 v[16:17], v[16:17], v[222:223] op_sel_hi:[1,0]
	v_pk_mul_f32 v[18:19], v[18:19], v[222:223] op_sel_hi:[1,0]
	v_pk_mul_f32 v[20:21], v[20:21], v[222:223] op_sel_hi:[1,0]
	v_pk_mul_f32 v[22:23], v[22:23], v[222:223] op_sel_hi:[1,0]
	v_pk_mul_f32 v[24:25], v[24:25], v[224:225] op_sel_hi:[1,0]
	v_pk_mul_f32 v[26:27], v[26:27], v[224:225] op_sel_hi:[1,0]
	v_pk_mul_f32 v[28:29], v[28:29], v[224:225] op_sel_hi:[1,0]
	v_pk_mul_f32 v[30:31], v[30:31], v[224:225] op_sel_hi:[1,0]
	v_pk_mul_f32 v[32:33], v[32:33], v[226:227] op_sel_hi:[1,0]
	v_pk_mul_f32 v[34:35], v[34:35], v[226:227] op_sel_hi:[1,0]
	v_pk_mul_f32 v[36:37], v[36:37], v[226:227] op_sel_hi:[1,0]
	v_pk_mul_f32 v[38:39], v[38:39], v[226:227] op_sel_hi:[1,0]
	s_branch .Ldq_rescret_19
